# hand-written software-pipelined FAST attention phase (QK/softmax/PV interleaved per 64-key block, 3-slot LDS rings)
# speedup vs baseline: 1.0816x; 1.0816x over previous
.Lat_entry:
	s_mov_b32 s26, 0
	s_mov_b32 s9, 0
	v_readlane_b32 s0, v254, 41
	v_readlane_b32 s4, v253, 0
	v_readlane_b32 s5, v255, 23
	s_mov_b32 s8, 0
	s_movk_i32 s6, 1536
	s_movk_i32 s1, 96
	s_cmp_eq_u32 s0, 0
	s_cbranch_scc1 .Lat_g1
	v_readlane_b32 s8, v254, 43
	v_readlane_b32 s4, v254, 44
	v_readlane_b32 s5, v254, 45
	s_movk_i32 s6, 192
	s_movk_i32 s1, 12
.Lat_g1:
	s_cmp_lg_u64 s[90:91], 0
	s_cselect_b32 s1, 0, s1
	s_mov_b32 s100, s1
	s_add_i32 s7, s6, s1
.Lat_unitloop:
	s_cmp_ge_i32 s4, s7
	s_cbranch_scc1 .Lat_done
	s_cmp_ge_i32 s4, s6
	s_cbranch_scc1 .Lat_ctx
	s_mul_i32 s0, s8, s6
	s_add_i32 s0, s0, s4
	s_mul_hi_u32 s1, s0, 0xaaaaaaab
	s_lshr_b32 s1, s1, 7
	s_mul_i32 s32, s1, 192
	s_sub_i32 s32, s0, s32
	s_lshr_b32 s56, s32, 4
	s_and_b32 s32, s32, 15
	s_lshl_b32 s76, s32, 8
	s_lshl_b32 s77, s1, 12
	s_add_i32 s77, s77, s76
	s_mov_b32 s78, 0
	s_mov_b32 s27, 32
	s_branch .Lat_ptrs
.Lat_ctx:
	s_mul_i32 s0, s8, s100
	s_sub_i32 s32, s4, s6
	s_add_i32 s0, s0, s32
	s_mul_hi_u32 s1, s0, 0xaaaaaaab
	s_lshr_b32 s1, s1, 3
	s_mul_i32 s32, s1, 12
	s_sub_i32 s56, s0, s32
	s_movk_i32 s76, 0x1000
	s_lshl_b32 s77, s1, 8
	s_add_i32 s77, s77, 0x8000
	s_movk_i32 s78, 0x1000
	s_mov_b32 s27, 0
.Lat_ptrs:
	s_mul_i32 s79, s77, 0x1440
	s_lshl_b32 s80, s77, 11
	s_cmp_ge_u32 s56, 6
	s_cbranch_scc1 .Lat_gq
	s_mul_i32 s81, s1, 6
	s_add_i32 s81, s81, s56
	s_mul_i32 s81, s81, 4352
	s_add_i32 s82, s81, s76
	s_mul_i32 s82, s82, 192
	s_add_u32 s82, s82, 0x108dd000
	s_add_u32 s10, s50, s82
	s_addc_u32 s11, s51, 0
	s_add_i32 s81, s81, s78
	s_mul_i32 s82, s81, 192
	s_add_u32 s82, s82, 0x12f1d000
	s_add_u32 s16, s50, s82
	s_addc_u32 s17, s51, 0
	s_lshl_b32 s82, s81, 7
	s_add_u32 s82, s82, 0x1555d000
	s_add_u32 s22, s50, s82
	s_addc_u32 s23, s51, 0
	s_lshl_b32 s83, s56, 7
	s_add_u32 s79, s79, s83
	s_add_u32 s79, s79, 97246272
	s_add_u32 s12, s50, s79
	s_addc_u32 s13, s51, 0
	s_add_u32 s80, s80, s83
	s_add_u32 s80, s80, 0x18bd000
	s_add_u32 s14, s50, s80
	s_addc_u32 s15, s51, 0
	s_branch .Lat_m_unit
.Lat_gq:
	s_add_i32 s56, s56, -6
	s_mul_i32 s81, s1, 6
	s_add_i32 s81, s81, s56
	s_mul_i32 s81, s81, 4352
	s_add_i32 s81, s81, s76
	s_lshl_b32 s81, s81, 7
	s_add_u32 s81, s81, 0x16edd000
	s_add_u32 s10, s50, s81
	s_addc_u32 s11, s51, 0
	s_cmp_ge_u32 s56, 3
	s_cselect_b32 s81, 1, 0
	s_lshl_b32 s82, s1, 1
	s_add_i32 s81, s81, s82
	s_mul_i32 s81, s81, 4352
	s_add_i32 s81, s81, s78
	s_lshl_b32 s81, s81, 7
	s_add_u32 s82, s81, 0x1885d000
	s_add_u32 s16, s50, s82
	s_addc_u32 s17, s51, 0
	s_add_u32 s82, s81, 0x190dd000
	s_add_u32 s22, s50, s82
	s_addc_u32 s23, s51, 0
	s_lshl_b32 s83, s56, 7
	s_add_u32 s79, s79, s83
	s_add_u32 s79, s79, 97247040
	s_add_u32 s12, s50, s79
	s_addc_u32 s13, s51, 0
	s_add_u32 s80, s80, s83
	s_add_u32 s80, s80, 25940736
	s_add_u32 s14, s50, s80
	s_addc_u32 s15, s51, 0
	s_branch .Lat_g_unit
.Lat_next:
	s_add_i32 s4, s4, s5
	s_add_i32 s9, s9, 1
	s_branch .Lat_unitloop
.Lat_m_unit:
	v_and_b32_e32 v32, 31, v143
	v_bfe_u32 v33, v143, 5, 1
	v_lshrrev_b32_e32 v34, 6, v143
	v_mul_u32_u24_e32 v237, 208, v32
	v_lshl_add_u32 v237, v33, 4, v237
	v_and_b32_e32 v35, 3, v143
	v_lshlrev_b32_e32 v238, 3, v35
	v_bfe_u32 v35, v143, 2, 2
	v_lshl_add_u32 v238, v35, 6, v238
	v_bfe_u32 v35, v143, 4, 1
	v_lshl_add_u32 v238, v35, 5, v238
	v_lshl_add_u32 v238, v33, 8, v238
	v_lshlrev_b32_e32 v232, 4, v143
	v_add_u32_e32 v239, 0x2000, v232
	v_add_u32_e32 v252, 0x4000, v232
	v_mov_b32_e32 v36, v143
	v_mul_u32_u24_e32 v37, 0xaaab, v36
	v_lshrrev_b32_e32 v37, 19, v37
	v_mul_u32_u24_e32 v38, 12, v37
	v_sub_u32_e32 v38, v36, v38
	v_mul_u32_u24_e32 v37, 208, v37
	v_lshl_add_u32 v179, v38, 4, v37
	v_add_u32_e32 v36, 512, v143
	v_mul_u32_u24_e32 v37, 0xaaab, v36
	v_lshrrev_b32_e32 v37, 19, v37
	v_mul_u32_u24_e32 v38, 12, v37
	v_sub_u32_e32 v38, v36, v38
	v_mul_u32_u24_e32 v37, 208, v37
	v_lshl_add_u32 v181, v38, 4, v37
	v_add_u32_e32 v36, 1024, v143
	v_mul_u32_u24_e32 v37, 0xaaab, v36
	v_lshrrev_b32_e32 v37, 19, v37
	v_mul_u32_u24_e32 v38, 12, v37
	v_sub_u32_e32 v38, v36, v38
	v_mul_u32_u24_e32 v37, 208, v37
	v_lshl_add_u32 v182, v38, 4, v37
	v_lshlrev_b32_e32 v183, 10, v34
	v_bfe_u32 v35, v143, 2, 1
	v_lshl_add_u32 v183, v35, 9, v183
	v_bfe_u32 v35, v143, 3, 3
	v_lshl_add_u32 v183, v35, 6, v183
	v_and_b32_e32 v35, 3, v143
	v_lshl_add_u32 v183, v35, 4, v183
	v_lshl_add_u32 v39, v34, 5, v32
	v_mul_u32_u24_e32 v36, 192, v39
	v_lshl_add_u32 v36, v33, 4, v36
	v_mul_u32_u24_e32 v133, 0x1440, v39
	v_lshl_add_u32 v133, v33, 3, v133
	v_lshlrev_b32_e32 v134, 11, v39
	v_lshl_add_u32 v134, v33, 3, v134
	global_load_dwordx4 v[184:187], v36, s[10:11] offset:0
	global_load_dwordx4 v[188:191], v36, s[10:11] offset:32
	global_load_dwordx4 v[192:195], v36, s[10:11] offset:64
	global_load_dwordx4 v[196:199], v36, s[10:11] offset:96
	global_load_dwordx4 v[200:203], v36, s[10:11] offset:128
	global_load_dwordx4 v[204:207], v36, s[10:11] offset:160
	global_load_dwordx4 v[208:211], v232, s[16:17]
	global_load_dwordx4 v[212:215], v239, s[16:17]
	global_load_dwordx4 v[216:219], v252, s[16:17]
	global_load_dwordx4 v[220:223], v232, s[22:23]
	global_load_dwordx4 v[224:227], v239, s[22:23]
	s_add_u32 s16, s16, 24576
	s_addc_u32 s17, s17, 0
	s_add_u32 s22, s22, 16384
	s_addc_u32 s23, s23, 0
	global_load_dwordx4 v[144:147], v232, s[16:17]
	global_load_dwordx4 v[148:151], v239, s[16:17]
	global_load_dwordx4 v[152:155], v252, s[16:17]
	s_add_u32 s16, s16, 24576
	s_addc_u32 s17, s17, 0
	s_mov_b32 s64, 0
	s_movk_i32 s65, 26624
	s_mov_b32 s68, 53248
	s_mov_b32 s69, 112640
	s_mov_b32 s70, 79872
	s_mov_b32 s71, 96256
	v_mov_b32_e32 v130, 0
	v_mov_b32_e32 v131, 0
	v_mov_b32_e32 v0, 0
	v_mov_b32_e32 v1, 0
	v_mov_b32_e32 v2, 0
	v_mov_b32_e32 v3, 0
	v_mov_b32_e32 v4, 0
	v_mov_b32_e32 v5, 0
	v_mov_b32_e32 v6, 0
	v_mov_b32_e32 v7, 0
	v_mov_b32_e32 v8, 0
	v_mov_b32_e32 v9, 0
	v_mov_b32_e32 v10, 0
	v_mov_b32_e32 v11, 0
	v_mov_b32_e32 v12, 0
	v_mov_b32_e32 v13, 0
	v_mov_b32_e32 v14, 0
	v_mov_b32_e32 v15, 0
	v_mov_b32_e32 v16, 0
	v_mov_b32_e32 v17, 0
	v_mov_b32_e32 v18, 0
	v_mov_b32_e32 v19, 0
	v_mov_b32_e32 v20, 0
	v_mov_b32_e32 v21, 0
	v_mov_b32_e32 v22, 0
	v_mov_b32_e32 v23, 0
	v_mov_b32_e32 v24, 0
	v_mov_b32_e32 v25, 0
	v_mov_b32_e32 v26, 0
	v_mov_b32_e32 v27, 0
	v_mov_b32_e32 v28, 0
	v_mov_b32_e32 v29, 0
	v_mov_b32_e32 v30, 0
	v_mov_b32_e32 v31, 0
	s_waitcnt vmcnt(3)
	ds_write_b128 v179, v[208:211]
	ds_write_b128 v181, v[212:215]
	ds_write_b128 v182, v[216:219]
	v_add_u32_e32 v128, 79872, v183
	ds_write_b128 v128, v[220:223]
	v_add_u32_e32 v128, 79872, v183
	ds_write_b128 v128, v[224:227] offset:8192
	global_load_dwordx4 v[208:211], v232, s[16:17]
	global_load_dwordx4 v[212:215], v239, s[16:17]
	global_load_dwordx4 v[216:219], v252, s[16:17]
	global_load_dwordx4 v[220:223], v232, s[22:23]
	global_load_dwordx4 v[224:227], v239, s[22:23]
	s_add_u32 s16, s16, 24576
	s_addc_u32 s17, s17, 0
	s_add_u32 s22, s22, 16384
	s_addc_u32 s23, s23, 0
	s_waitcnt vmcnt(5)
	v_add_u32_e32 v128, 26624, v179
	ds_write_b128 v128, v[144:147]
	v_add_u32_e32 v128, 26624, v181
	ds_write_b128 v128, v[148:151]
	v_add_u32_e32 v128, 26624, v182
	ds_write_b128 v128, v[152:155]
	v_add_u32_e32 v140, s64, v237
	s_waitcnt lgkmcnt(0)
	s_barrier
	ds_read_b128 v[144:147], v140 offset:0
	ds_read_b128 v[148:151], v140 offset:32
	ds_read_b128 v[152:155], v140 offset:64
	ds_read_b128 v[156:159], v140 offset:96
	ds_read_b128 v[160:163], v140 offset:128
	ds_read_b128 v[164:167], v140 offset:160
	s_waitcnt lgkmcnt(5)
	v_mfma_f32_32x32x16_bf16 v[32:47], v[144:147], v[184:187], 0
	ds_read_b128 v[168:171], v140 offset:6656
	s_waitcnt lgkmcnt(5)
	v_mfma_f32_32x32x16_bf16 v[32:47], v[148:151], v[188:191], v[32:47]
	ds_read_b128 v[172:175], v140 offset:6688
	s_waitcnt lgkmcnt(5)
	v_mfma_f32_32x32x16_bf16 v[32:47], v[152:155], v[192:195], v[32:47]
	ds_read_b128 v[144:147], v140 offset:6720
	s_waitcnt lgkmcnt(5)
	v_mfma_f32_32x32x16_bf16 v[32:47], v[156:159], v[196:199], v[32:47]
	ds_read_b128 v[148:151], v140 offset:6752
	s_waitcnt lgkmcnt(5)
	v_mfma_f32_32x32x16_bf16 v[32:47], v[160:163], v[200:203], v[32:47]
	ds_read_b128 v[152:155], v140 offset:6784
	s_waitcnt lgkmcnt(5)
	v_mfma_f32_32x32x16_bf16 v[32:47], v[164:167], v[204:207], v[32:47]
	ds_read_b128 v[156:159], v140 offset:6816
	s_waitcnt lgkmcnt(5)
	v_mfma_f32_32x32x16_bf16 v[48:63], v[168:171], v[184:187], 0
	s_waitcnt lgkmcnt(4)
	v_mfma_f32_32x32x16_bf16 v[48:63], v[172:175], v[188:191], v[48:63]
	s_waitcnt lgkmcnt(3)
	v_mfma_f32_32x32x16_bf16 v[48:63], v[144:147], v[192:195], v[48:63]
	s_waitcnt lgkmcnt(2)
	v_mfma_f32_32x32x16_bf16 v[48:63], v[148:151], v[196:199], v[48:63]
	s_waitcnt lgkmcnt(1)
	v_mfma_f32_32x32x16_bf16 v[48:63], v[152:155], v[200:203], v[48:63]
	s_waitcnt lgkmcnt(0)
	v_mfma_f32_32x32x16_bf16 v[48:63], v[156:159], v[204:207], v[48:63]
	s_nop 7
	s_nop 3
	v_add_u32_e32 v140, s64, v237
	v_add_u32_e32 v141, s65, v237
	v_add_u32_e32 v176, s69, v238
	v_add_u32_e32 v177, s70, v238
	ds_read_b128 v[160:163], v140 offset:13312
	ds_read_b128 v[164:167], v140 offset:13344
	ds_read_b128 v[168:171], v140 offset:13376
	ds_read_b128 v[172:175], v140 offset:13408
	ds_read_b128 v[144:147], v140 offset:13440
	ds_read_b128 v[148:151], v140 offset:13472
	s_waitcnt lgkmcnt(5)
	v_mfma_f32_32x32x16_bf16 v[64:79], v[160:163], v[184:187], 0
	ds_read_b128 v[152:155], v140 offset:19968
	v_exp_f32_e32 v32, v32
	v_exp_f32_e32 v33, v33
	v_add_f32_e32 v130, v130, v32
	v_add_f32_e32 v131, v131, v33
	v_cvt_pk_bf16_f32 v96, v32, v33
	v_exp_f32_e32 v34, v34
	v_exp_f32_e32 v35, v35
	s_waitcnt vmcnt(4)
	v_add_u32_e32 v128, s68, v179
	ds_write_b128 v128, v[208:211]
	global_load_dwordx4 v[208:211], v232, s[16:17]
	s_waitcnt lgkmcnt(6)
	v_mfma_f32_32x32x16_bf16 v[64:79], v[164:167], v[188:191], v[64:79]
	ds_read_b128 v[156:159], v140 offset:20000
	v_add_f32_e32 v130, v130, v34
	v_add_f32_e32 v131, v131, v35
	v_cvt_pk_bf16_f32 v97, v34, v35
	v_exp_f32_e32 v36, v36
	v_exp_f32_e32 v37, v37
	v_add_f32_e32 v130, v130, v36
	v_add_f32_e32 v131, v131, v37
	s_waitcnt vmcnt(4)
	v_add_u32_e32 v128, s68, v181
	ds_write_b128 v128, v[212:215]
	global_load_dwordx4 v[212:215], v239, s[16:17]
	s_waitcnt lgkmcnt(7)
	v_mfma_f32_32x32x16_bf16 v[64:79], v[168:171], v[192:195], v[64:79]
	ds_read_b128 v[160:163], v140 offset:20032
	v_cvt_pk_bf16_f32 v98, v36, v37
	v_exp_f32_e32 v38, v38
	v_exp_f32_e32 v39, v39
	v_add_f32_e32 v130, v130, v38
	v_add_f32_e32 v131, v131, v39
	v_cvt_pk_bf16_f32 v99, v38, v39
	s_waitcnt vmcnt(4)
	v_add_u32_e32 v128, s68, v182
	ds_write_b128 v128, v[216:219]
	global_load_dwordx4 v[216:219], v252, s[16:17]
	s_waitcnt lgkmcnt(8)
	v_mfma_f32_32x32x16_bf16 v[64:79], v[172:175], v[196:199], v[64:79]
	ds_read_b128 v[164:167], v140 offset:20064
	v_exp_f32_e32 v40, v40
	v_exp_f32_e32 v41, v41
	v_add_f32_e32 v130, v130, v40
	v_add_f32_e32 v131, v131, v41
	v_cvt_pk_bf16_f32 v100, v40, v41
	v_exp_f32_e32 v42, v42
	v_exp_f32_e32 v43, v43
	s_waitcnt vmcnt(4)
	v_add_u32_e32 v128, s71, v183
	ds_write_b128 v128, v[220:223]
	global_load_dwordx4 v[220:223], v232, s[22:23]
	s_waitcnt lgkmcnt(9)
	v_mfma_f32_32x32x16_bf16 v[64:79], v[144:147], v[200:203], v[64:79]
	ds_read_b128 v[168:171], v140 offset:20096
	v_add_f32_e32 v130, v130, v42
	v_add_f32_e32 v131, v131, v43
	v_cvt_pk_bf16_f32 v101, v42, v43
	v_exp_f32_e32 v44, v44
	v_exp_f32_e32 v45, v45
	v_add_f32_e32 v130, v130, v44
	v_add_f32_e32 v131, v131, v45
	s_waitcnt vmcnt(4)
	v_add_u32_e32 v128, s71, v183
	ds_write_b128 v128, v[224:227] offset:8192
	global_load_dwordx4 v[224:227], v239, s[22:23]
	s_waitcnt lgkmcnt(10)
	v_mfma_f32_32x32x16_bf16 v[64:79], v[148:151], v[204:207], v[64:79]
	ds_read_b128 v[172:175], v140 offset:20128
	v_cvt_pk_bf16_f32 v102, v44, v45
	v_exp_f32_e32 v46, v46
	v_exp_f32_e32 v47, v47
	v_add_f32_e32 v130, v130, v46
	v_add_f32_e32 v131, v131, v47
	v_cvt_pk_bf16_f32 v103, v46, v47
	s_waitcnt lgkmcnt(10)
	v_mfma_f32_32x32x16_bf16 v[80:95], v[152:155], v[184:187], 0
	ds_read_b128 v[144:147], v141 offset:0
	v_exp_f32_e32 v48, v48
	v_exp_f32_e32 v49, v49
	v_add_f32_e32 v130, v130, v48
	v_add_f32_e32 v131, v131, v49
	v_cvt_pk_bf16_f32 v104, v48, v49
	v_exp_f32_e32 v50, v50
	v_exp_f32_e32 v51, v51
	s_waitcnt lgkmcnt(9)
	v_mfma_f32_32x32x16_bf16 v[80:95], v[156:159], v[188:191], v[80:95]
	ds_read_b128 v[148:151], v141 offset:32
	v_add_f32_e32 v130, v130, v50
	v_add_f32_e32 v131, v131, v51
	v_cvt_pk_bf16_f32 v105, v50, v51
	v_exp_f32_e32 v52, v52
	v_exp_f32_e32 v53, v53
	v_add_f32_e32 v130, v130, v52
	v_add_f32_e32 v131, v131, v53
	s_waitcnt lgkmcnt(8)
	v_mfma_f32_32x32x16_bf16 v[80:95], v[160:163], v[192:195], v[80:95]
	ds_read_b128 v[152:155], v141 offset:64
	v_cvt_pk_bf16_f32 v106, v52, v53
	v_exp_f32_e32 v54, v54
	v_exp_f32_e32 v55, v55
	v_add_f32_e32 v130, v130, v54
	v_add_f32_e32 v131, v131, v55
	v_cvt_pk_bf16_f32 v107, v54, v55
	s_waitcnt lgkmcnt(7)
	v_mfma_f32_32x32x16_bf16 v[80:95], v[164:167], v[196:199], v[80:95]
	ds_read_b128 v[156:159], v141 offset:96
	v_exp_f32_e32 v56, v56
	v_exp_f32_e32 v57, v57
	v_add_f32_e32 v130, v130, v56
	v_add_f32_e32 v131, v131, v57
	v_cvt_pk_bf16_f32 v108, v56, v57
	v_exp_f32_e32 v58, v58
	v_exp_f32_e32 v59, v59
	s_waitcnt lgkmcnt(6)
	v_mfma_f32_32x32x16_bf16 v[80:95], v[168:171], v[200:203], v[80:95]
	ds_read_b128 v[160:163], v141 offset:128
	v_add_f32_e32 v130, v130, v58
	v_add_f32_e32 v131, v131, v59
	v_cvt_pk_bf16_f32 v109, v58, v59
	v_exp_f32_e32 v60, v60
	v_exp_f32_e32 v61, v61
	v_add_f32_e32 v130, v130, v60
	v_add_f32_e32 v131, v131, v61
	s_waitcnt lgkmcnt(5)
	v_mfma_f32_32x32x16_bf16 v[80:95], v[172:175], v[204:207], v[80:95]
	ds_read_b128 v[164:167], v141 offset:160
	v_cvt_pk_bf16_f32 v110, v60, v61
	v_exp_f32_e32 v62, v62
	v_exp_f32_e32 v63, v63
	v_add_f32_e32 v130, v130, v62
	v_add_f32_e32 v131, v131, v63
	v_cvt_pk_bf16_f32 v111, v62, v63
	s_add_u32 s16, s16, 24576
	s_addc_u32 s17, s17, 0
	s_add_u32 s22, s22, 16384
	s_addc_u32 s23, s23, 0
	s_waitcnt lgkmcnt(5)
	v_mfma_f32_32x32x16_bf16 v[32:47], v[144:147], v[184:187], 0
	ds_read_b128 v[168:171], v141 offset:6656
	v_exp_f32_e32 v64, v64
	v_exp_f32_e32 v65, v65
	v_add_f32_e32 v130, v130, v64
	v_add_f32_e32 v131, v131, v65
	s_waitcnt lgkmcnt(5)
	v_mfma_f32_32x32x16_bf16 v[32:47], v[148:151], v[188:191], v[32:47]
	ds_read_b128 v[172:175], v141 offset:6688
	v_cvt_pk_bf16_f32 v112, v64, v65
	v_exp_f32_e32 v66, v66
	v_exp_f32_e32 v67, v67
	v_add_f32_e32 v130, v130, v66
	s_waitcnt lgkmcnt(5)
	v_mfma_f32_32x32x16_bf16 v[32:47], v[152:155], v[192:195], v[32:47]
	ds_read_b128 v[144:147], v141 offset:6720
	v_add_f32_e32 v131, v131, v67
	v_cvt_pk_bf16_f32 v113, v66, v67
	v_exp_f32_e32 v68, v68
	v_exp_f32_e32 v69, v69
	s_waitcnt lgkmcnt(5)
	v_mfma_f32_32x32x16_bf16 v[32:47], v[156:159], v[196:199], v[32:47]
	ds_read_b128 v[148:151], v141 offset:6752
	v_add_f32_e32 v130, v130, v68
	v_add_f32_e32 v131, v131, v69
	v_cvt_pk_bf16_f32 v114, v68, v69
	v_exp_f32_e32 v70, v70
	s_waitcnt lgkmcnt(5)
	v_mfma_f32_32x32x16_bf16 v[32:47], v[160:163], v[200:203], v[32:47]
	ds_read_b128 v[152:155], v141 offset:6784
	v_exp_f32_e32 v71, v71
	v_add_f32_e32 v130, v130, v70
	v_add_f32_e32 v131, v131, v71
	v_cvt_pk_bf16_f32 v115, v70, v71
	s_waitcnt lgkmcnt(5)
	v_mfma_f32_32x32x16_bf16 v[32:47], v[164:167], v[204:207], v[32:47]
	ds_read_b128 v[156:159], v141 offset:6816
	v_exp_f32_e32 v72, v72
	v_exp_f32_e32 v73, v73
	v_add_f32_e32 v130, v130, v72
	v_add_f32_e32 v131, v131, v73
	s_waitcnt lgkmcnt(5)
	v_mfma_f32_32x32x16_bf16 v[48:63], v[168:171], v[184:187], 0
	ds_read_b64_tr_b16 v[160:161], v177 offset:0
	ds_read_b64_tr_b16 v[162:163], v177 offset:1024
	v_cvt_pk_bf16_f32 v116, v72, v73
	v_exp_f32_e32 v74, v74
	v_exp_f32_e32 v75, v75
	v_add_f32_e32 v130, v130, v74
	s_waitcnt lgkmcnt(6)
	v_mfma_f32_32x32x16_bf16 v[48:63], v[172:175], v[188:191], v[48:63]
	ds_read_b64_tr_b16 v[164:165], v177 offset:512
	ds_read_b64_tr_b16 v[166:167], v177 offset:1536
	v_add_f32_e32 v131, v131, v75
	v_cvt_pk_bf16_f32 v117, v74, v75
	v_exp_f32_e32 v76, v76
	v_exp_f32_e32 v77, v77
	s_waitcnt lgkmcnt(7)
	v_mfma_f32_32x32x16_bf16 v[48:63], v[144:147], v[192:195], v[48:63]
	ds_read_b64_tr_b16 v[168:169], v177 offset:2048
	ds_read_b64_tr_b16 v[170:171], v177 offset:3072
	v_add_f32_e32 v130, v130, v76
	v_add_f32_e32 v131, v131, v77
	v_cvt_pk_bf16_f32 v118, v76, v77
	v_exp_f32_e32 v78, v78
	s_waitcnt lgkmcnt(8)
	v_mfma_f32_32x32x16_bf16 v[48:63], v[148:151], v[196:199], v[48:63]
	ds_read_b64_tr_b16 v[172:173], v177 offset:2560
	ds_read_b64_tr_b16 v[174:175], v177 offset:3584
	v_exp_f32_e32 v79, v79
	v_add_f32_e32 v130, v130, v78
	v_add_f32_e32 v131, v131, v79
	v_cvt_pk_bf16_f32 v119, v78, v79
	s_waitcnt lgkmcnt(9)
	v_mfma_f32_32x32x16_bf16 v[48:63], v[152:155], v[200:203], v[48:63]
	ds_read_b64_tr_b16 v[144:145], v177 offset:4096
	ds_read_b64_tr_b16 v[146:147], v177 offset:5120
	v_exp_f32_e32 v80, v80
	v_exp_f32_e32 v81, v81
	v_add_f32_e32 v130, v130, v80
	v_add_f32_e32 v131, v131, v81
	s_waitcnt lgkmcnt(10)
	v_mfma_f32_32x32x16_bf16 v[48:63], v[156:159], v[204:207], v[48:63]
	ds_read_b64_tr_b16 v[148:149], v177 offset:4608
	ds_read_b64_tr_b16 v[150:151], v177 offset:5632
	v_cvt_pk_bf16_f32 v120, v80, v81
	v_exp_f32_e32 v82, v82
	v_exp_f32_e32 v83, v83
	v_add_f32_e32 v130, v130, v82
	s_waitcnt lgkmcnt(10)
	v_mfma_f32_32x32x16_bf16 v[0:15], v[160:163], v[96:99], v[0:15]
	ds_read_b64_tr_b16 v[152:153], v177 offset:6144
	ds_read_b64_tr_b16 v[154:155], v177 offset:7168
	v_add_f32_e32 v131, v131, v83
	v_cvt_pk_bf16_f32 v121, v82, v83
	v_exp_f32_e32 v84, v84
	v_exp_f32_e32 v85, v85
	s_waitcnt lgkmcnt(10)
	v_mfma_f32_32x32x16_bf16 v[16:31], v[164:167], v[96:99], v[16:31]
	ds_read_b64_tr_b16 v[156:157], v177 offset:6656
	ds_read_b64_tr_b16 v[158:159], v177 offset:7680
	v_add_f32_e32 v130, v130, v84
	v_add_f32_e32 v131, v131, v85
	v_cvt_pk_bf16_f32 v122, v84, v85
	v_exp_f32_e32 v86, v86
	s_waitcnt lgkmcnt(10)
	v_mfma_f32_32x32x16_bf16 v[0:15], v[168:171], v[100:103], v[0:15]
	ds_read_b128 v[160:163], v141 offset:13312
	v_exp_f32_e32 v87, v87
	v_add_f32_e32 v130, v130, v86
	v_add_f32_e32 v131, v131, v87
	v_cvt_pk_bf16_f32 v123, v86, v87
	s_waitcnt lgkmcnt(9)
	v_mfma_f32_32x32x16_bf16 v[16:31], v[172:175], v[100:103], v[16:31]
	ds_read_b128 v[164:167], v141 offset:13344
	v_exp_f32_e32 v88, v88
	v_exp_f32_e32 v89, v89
	v_add_f32_e32 v130, v130, v88
	v_add_f32_e32 v131, v131, v89
	s_waitcnt lgkmcnt(8)
	v_mfma_f32_32x32x16_bf16 v[0:15], v[144:147], v[104:107], v[0:15]
	ds_read_b128 v[168:171], v141 offset:13376
	v_cvt_pk_bf16_f32 v124, v88, v89
	v_exp_f32_e32 v90, v90
	v_exp_f32_e32 v91, v91
	v_add_f32_e32 v130, v130, v90
	s_waitcnt lgkmcnt(7)
	v_mfma_f32_32x32x16_bf16 v[16:31], v[148:151], v[104:107], v[16:31]
	ds_read_b128 v[172:175], v141 offset:13408
	v_add_f32_e32 v131, v131, v91
	v_cvt_pk_bf16_f32 v125, v90, v91
	v_exp_f32_e32 v92, v92
	v_exp_f32_e32 v93, v93
	s_waitcnt lgkmcnt(6)
	v_mfma_f32_32x32x16_bf16 v[0:15], v[152:155], v[108:111], v[0:15]
	ds_read_b128 v[144:147], v141 offset:13440
	v_add_f32_e32 v130, v130, v92
	v_add_f32_e32 v131, v131, v93
	v_cvt_pk_bf16_f32 v126, v92, v93
	v_exp_f32_e32 v94, v94
	s_waitcnt lgkmcnt(5)
	v_mfma_f32_32x32x16_bf16 v[16:31], v[156:159], v[108:111], v[16:31]
	ds_read_b128 v[148:151], v141 offset:13472
	v_exp_f32_e32 v95, v95
	v_add_f32_e32 v130, v130, v94
	v_add_f32_e32 v131, v131, v95
	v_cvt_pk_bf16_f32 v127, v94, v95
	s_mov_b32 s0, s64
	s_mov_b32 s64, s65
	s_mov_b32 s65, s68
	s_mov_b32 s68, s0
	s_mov_b32 s0, s69
	s_mov_b32 s69, s70
	s_mov_b32 s70, s71
	s_mov_b32 s71, s0
	s_barrier
	s_cmp_eq_u32 s27, 0
	s_cbranch_scc1 .Lat_m_last
.Lat_m_loop:
	v_add_u32_e32 v140, s64, v237
	v_add_u32_e32 v141, s65, v237
	v_add_u32_e32 v176, s69, v238
	v_add_u32_e32 v177, s70, v238
	s_waitcnt lgkmcnt(5)
	v_mfma_f32_32x32x16_bf16 v[64:79], v[160:163], v[184:187], 0
	ds_read_b128 v[152:155], v140 offset:19968
	v_exp_f32_e32 v32, v32
	v_exp_f32_e32 v33, v33
	v_add_f32_e32 v130, v130, v32
	v_add_f32_e32 v131, v131, v33
	s_waitcnt vmcnt(4)
	v_add_u32_e32 v128, s68, v179
	ds_write_b128 v128, v[208:211]
	global_load_dwordx4 v[208:211], v232, s[16:17]
	s_waitcnt lgkmcnt(6)
	v_mfma_f32_32x32x16_bf16 v[64:79], v[164:167], v[188:191], v[64:79]
	ds_read_b128 v[156:159], v140 offset:20000
	v_cvt_pk_bf16_f32 v96, v32, v33
	v_exp_f32_e32 v34, v34
	v_exp_f32_e32 v35, v35
	v_add_f32_e32 v130, v130, v34
	s_waitcnt vmcnt(4)
	v_add_u32_e32 v128, s68, v181
	ds_write_b128 v128, v[212:215]
	global_load_dwordx4 v[212:215], v239, s[16:17]
	s_waitcnt lgkmcnt(7)
	v_mfma_f32_32x32x16_bf16 v[64:79], v[168:171], v[192:195], v[64:79]
	ds_read_b128 v[160:163], v140 offset:20032
	v_add_f32_e32 v131, v131, v35
	v_cvt_pk_bf16_f32 v97, v34, v35
	v_exp_f32_e32 v36, v36
	v_exp_f32_e32 v37, v37
	s_waitcnt vmcnt(4)
	v_add_u32_e32 v128, s68, v182
	ds_write_b128 v128, v[216:219]
	global_load_dwordx4 v[216:219], v252, s[16:17]
	s_waitcnt lgkmcnt(8)
	v_mfma_f32_32x32x16_bf16 v[64:79], v[172:175], v[196:199], v[64:79]
	ds_read_b128 v[164:167], v140 offset:20064
	v_add_f32_e32 v130, v130, v36
	v_add_f32_e32 v131, v131, v37
	v_cvt_pk_bf16_f32 v98, v36, v37
	v_exp_f32_e32 v38, v38
	s_waitcnt vmcnt(4)
	v_add_u32_e32 v128, s71, v183
	ds_write_b128 v128, v[220:223]
	global_load_dwordx4 v[220:223], v232, s[22:23]
	s_waitcnt lgkmcnt(9)
	v_mfma_f32_32x32x16_bf16 v[64:79], v[144:147], v[200:203], v[64:79]
	ds_read_b128 v[168:171], v140 offset:20096
	v_exp_f32_e32 v39, v39
	v_add_f32_e32 v130, v130, v38
	v_add_f32_e32 v131, v131, v39
	v_cvt_pk_bf16_f32 v99, v38, v39
	s_waitcnt vmcnt(4)
	v_add_u32_e32 v128, s71, v183
	ds_write_b128 v128, v[224:227] offset:8192
	global_load_dwordx4 v[224:227], v239, s[22:23]
	s_waitcnt lgkmcnt(10)
	v_mfma_f32_32x32x16_bf16 v[64:79], v[148:151], v[204:207], v[64:79]
	ds_read_b128 v[172:175], v140 offset:20128
	v_exp_f32_e32 v40, v40
	v_exp_f32_e32 v41, v41
	v_add_f32_e32 v130, v130, v40
	v_add_f32_e32 v131, v131, v41
	s_waitcnt lgkmcnt(10)
	v_mfma_f32_32x32x16_bf16 v[80:95], v[152:155], v[184:187], 0
	ds_read_b64_tr_b16 v[144:145], v176 offset:8192
	ds_read_b64_tr_b16 v[146:147], v176 offset:9216
	v_cvt_pk_bf16_f32 v100, v40, v41
	v_exp_f32_e32 v42, v42
	v_exp_f32_e32 v43, v43
	v_add_f32_e32 v130, v130, v42
	s_waitcnt lgkmcnt(10)
	v_mfma_f32_32x32x16_bf16 v[80:95], v[156:159], v[188:191], v[80:95]
	ds_read_b64_tr_b16 v[148:149], v176 offset:8704
	ds_read_b64_tr_b16 v[150:151], v176 offset:9728
	v_add_f32_e32 v131, v131, v43
	v_cvt_pk_bf16_f32 v101, v42, v43
	v_exp_f32_e32 v44, v44
	v_exp_f32_e32 v45, v45
	s_waitcnt lgkmcnt(10)
	v_mfma_f32_32x32x16_bf16 v[80:95], v[160:163], v[192:195], v[80:95]
	ds_read_b64_tr_b16 v[152:153], v176 offset:10240
	ds_read_b64_tr_b16 v[154:155], v176 offset:11264
	v_add_f32_e32 v130, v130, v44
	v_add_f32_e32 v131, v131, v45
	v_cvt_pk_bf16_f32 v102, v44, v45
	v_exp_f32_e32 v46, v46
	s_waitcnt lgkmcnt(10)
	v_mfma_f32_32x32x16_bf16 v[80:95], v[164:167], v[196:199], v[80:95]
	ds_read_b64_tr_b16 v[156:157], v176 offset:10752
	ds_read_b64_tr_b16 v[158:159], v176 offset:11776
	v_exp_f32_e32 v47, v47
	v_add_f32_e32 v130, v130, v46
	v_add_f32_e32 v131, v131, v47
	v_cvt_pk_bf16_f32 v103, v46, v47
	s_waitcnt lgkmcnt(10)
	v_mfma_f32_32x32x16_bf16 v[80:95], v[168:171], v[200:203], v[80:95]
	ds_read_b64_tr_b16 v[160:161], v176 offset:12288
	ds_read_b64_tr_b16 v[162:163], v176 offset:13312
	v_exp_f32_e32 v48, v48
	v_exp_f32_e32 v49, v49
	v_add_f32_e32 v130, v130, v48
	v_add_f32_e32 v131, v131, v49
	s_waitcnt lgkmcnt(10)
	v_mfma_f32_32x32x16_bf16 v[80:95], v[172:175], v[204:207], v[80:95]
	ds_read_b64_tr_b16 v[164:165], v176 offset:12800
	ds_read_b64_tr_b16 v[166:167], v176 offset:13824
	v_cvt_pk_bf16_f32 v104, v48, v49
	v_exp_f32_e32 v50, v50
	v_exp_f32_e32 v51, v51
	v_add_f32_e32 v130, v130, v50
	s_waitcnt lgkmcnt(10)
	v_mfma_f32_32x32x16_bf16 v[0:15], v[144:147], v[112:115], v[0:15]
	ds_read_b64_tr_b16 v[168:169], v176 offset:14336
	ds_read_b64_tr_b16 v[170:171], v176 offset:15360
	v_add_f32_e32 v131, v131, v51
	v_cvt_pk_bf16_f32 v105, v50, v51
	v_exp_f32_e32 v52, v52
	v_exp_f32_e32 v53, v53
	s_waitcnt lgkmcnt(10)
	v_mfma_f32_32x32x16_bf16 v[16:31], v[148:151], v[112:115], v[16:31]
	ds_read_b64_tr_b16 v[172:173], v176 offset:14848
	ds_read_b64_tr_b16 v[174:175], v176 offset:15872
	v_add_f32_e32 v130, v130, v52
	v_add_f32_e32 v131, v131, v53
	v_cvt_pk_bf16_f32 v106, v52, v53
	v_exp_f32_e32 v54, v54
	s_waitcnt lgkmcnt(10)
	v_mfma_f32_32x32x16_bf16 v[0:15], v[152:155], v[116:119], v[0:15]
	ds_read_b128 v[144:147], v141 offset:0
	v_exp_f32_e32 v55, v55
	v_add_f32_e32 v130, v130, v54
	v_add_f32_e32 v131, v131, v55
	v_cvt_pk_bf16_f32 v107, v54, v55
	s_waitcnt lgkmcnt(9)
	v_mfma_f32_32x32x16_bf16 v[16:31], v[156:159], v[116:119], v[16:31]
	ds_read_b128 v[148:151], v141 offset:32
	v_exp_f32_e32 v56, v56
	v_exp_f32_e32 v57, v57
	v_add_f32_e32 v130, v130, v56
	v_add_f32_e32 v131, v131, v57
	s_waitcnt lgkmcnt(8)
	v_mfma_f32_32x32x16_bf16 v[0:15], v[160:163], v[120:123], v[0:15]
	ds_read_b128 v[152:155], v141 offset:64
	v_cvt_pk_bf16_f32 v108, v56, v57
	v_exp_f32_e32 v58, v58
	v_exp_f32_e32 v59, v59
	v_add_f32_e32 v130, v130, v58
	s_waitcnt lgkmcnt(7)
	v_mfma_f32_32x32x16_bf16 v[16:31], v[164:167], v[120:123], v[16:31]
	ds_read_b128 v[156:159], v141 offset:96
	v_add_f32_e32 v131, v131, v59
	v_cvt_pk_bf16_f32 v109, v58, v59
	v_exp_f32_e32 v60, v60
	v_exp_f32_e32 v61, v61
	s_waitcnt lgkmcnt(6)
	v_mfma_f32_32x32x16_bf16 v[0:15], v[168:171], v[124:127], v[0:15]
	ds_read_b128 v[160:163], v141 offset:128
	v_add_f32_e32 v130, v130, v60
	v_add_f32_e32 v131, v131, v61
	v_cvt_pk_bf16_f32 v110, v60, v61
	v_exp_f32_e32 v62, v62
	s_waitcnt lgkmcnt(5)
	v_mfma_f32_32x32x16_bf16 v[16:31], v[172:175], v[124:127], v[16:31]
	ds_read_b128 v[164:167], v141 offset:160
	v_exp_f32_e32 v63, v63
	v_add_f32_e32 v130, v130, v62
	v_add_f32_e32 v131, v131, v63
	v_cvt_pk_bf16_f32 v111, v62, v63
	s_add_u32 s16, s16, 24576
	s_addc_u32 s17, s17, 0
	s_add_u32 s22, s22, 16384
	s_addc_u32 s23, s23, 0
	s_waitcnt lgkmcnt(5)
	v_mfma_f32_32x32x16_bf16 v[32:47], v[144:147], v[184:187], 0
	ds_read_b128 v[168:171], v141 offset:6656
	v_exp_f32_e32 v64, v64
	v_exp_f32_e32 v65, v65
	v_add_f32_e32 v130, v130, v64
	v_add_f32_e32 v131, v131, v65
	s_waitcnt lgkmcnt(5)
	v_mfma_f32_32x32x16_bf16 v[32:47], v[148:151], v[188:191], v[32:47]
	ds_read_b128 v[172:175], v141 offset:6688
	v_cvt_pk_bf16_f32 v112, v64, v65
	v_exp_f32_e32 v66, v66
	v_exp_f32_e32 v67, v67
	v_add_f32_e32 v130, v130, v66
	s_waitcnt lgkmcnt(5)
	v_mfma_f32_32x32x16_bf16 v[32:47], v[152:155], v[192:195], v[32:47]
	ds_read_b128 v[144:147], v141 offset:6720
	v_add_f32_e32 v131, v131, v67
	v_cvt_pk_bf16_f32 v113, v66, v67
	v_exp_f32_e32 v68, v68
	v_exp_f32_e32 v69, v69
	s_waitcnt lgkmcnt(5)
	v_mfma_f32_32x32x16_bf16 v[32:47], v[156:159], v[196:199], v[32:47]
	ds_read_b128 v[148:151], v141 offset:6752
	v_add_f32_e32 v130, v130, v68
	v_add_f32_e32 v131, v131, v69
	v_cvt_pk_bf16_f32 v114, v68, v69
	v_exp_f32_e32 v70, v70
	s_waitcnt lgkmcnt(5)
	v_mfma_f32_32x32x16_bf16 v[32:47], v[160:163], v[200:203], v[32:47]
	ds_read_b128 v[152:155], v141 offset:6784
	v_exp_f32_e32 v71, v71
	v_add_f32_e32 v130, v130, v70
	v_add_f32_e32 v131, v131, v71
	v_cvt_pk_bf16_f32 v115, v70, v71
	s_waitcnt lgkmcnt(5)
	v_mfma_f32_32x32x16_bf16 v[32:47], v[164:167], v[204:207], v[32:47]
	ds_read_b128 v[156:159], v141 offset:6816
	v_exp_f32_e32 v72, v72
	v_exp_f32_e32 v73, v73
	v_add_f32_e32 v130, v130, v72
	v_add_f32_e32 v131, v131, v73
	s_waitcnt lgkmcnt(5)
	v_mfma_f32_32x32x16_bf16 v[48:63], v[168:171], v[184:187], 0
	ds_read_b64_tr_b16 v[160:161], v177 offset:0
	ds_read_b64_tr_b16 v[162:163], v177 offset:1024
	v_cvt_pk_bf16_f32 v116, v72, v73
	v_exp_f32_e32 v74, v74
	v_exp_f32_e32 v75, v75
	v_add_f32_e32 v130, v130, v74
	s_waitcnt lgkmcnt(6)
	v_mfma_f32_32x32x16_bf16 v[48:63], v[172:175], v[188:191], v[48:63]
	ds_read_b64_tr_b16 v[164:165], v177 offset:512
	ds_read_b64_tr_b16 v[166:167], v177 offset:1536
	v_add_f32_e32 v131, v131, v75
	v_cvt_pk_bf16_f32 v117, v74, v75
	v_exp_f32_e32 v76, v76
	v_exp_f32_e32 v77, v77
	s_waitcnt lgkmcnt(7)
	v_mfma_f32_32x32x16_bf16 v[48:63], v[144:147], v[192:195], v[48:63]
	ds_read_b64_tr_b16 v[168:169], v177 offset:2048
	ds_read_b64_tr_b16 v[170:171], v177 offset:3072
	v_add_f32_e32 v130, v130, v76
	v_add_f32_e32 v131, v131, v77
	v_cvt_pk_bf16_f32 v118, v76, v77
	v_exp_f32_e32 v78, v78
	s_waitcnt lgkmcnt(8)
	v_mfma_f32_32x32x16_bf16 v[48:63], v[148:151], v[196:199], v[48:63]
	ds_read_b64_tr_b16 v[172:173], v177 offset:2560
	ds_read_b64_tr_b16 v[174:175], v177 offset:3584
	v_exp_f32_e32 v79, v79
	v_add_f32_e32 v130, v130, v78
	v_add_f32_e32 v131, v131, v79
	v_cvt_pk_bf16_f32 v119, v78, v79
	s_waitcnt lgkmcnt(9)
	v_mfma_f32_32x32x16_bf16 v[48:63], v[152:155], v[200:203], v[48:63]
	ds_read_b64_tr_b16 v[144:145], v177 offset:4096
	ds_read_b64_tr_b16 v[146:147], v177 offset:5120
	v_exp_f32_e32 v80, v80
	v_exp_f32_e32 v81, v81
	v_add_f32_e32 v130, v130, v80
	v_add_f32_e32 v131, v131, v81
	s_waitcnt lgkmcnt(10)
	v_mfma_f32_32x32x16_bf16 v[48:63], v[156:159], v[204:207], v[48:63]
	ds_read_b64_tr_b16 v[148:149], v177 offset:4608
	ds_read_b64_tr_b16 v[150:151], v177 offset:5632
	v_cvt_pk_bf16_f32 v120, v80, v81
	v_exp_f32_e32 v82, v82
	v_exp_f32_e32 v83, v83
	v_add_f32_e32 v130, v130, v82
	s_waitcnt lgkmcnt(10)
	v_mfma_f32_32x32x16_bf16 v[0:15], v[160:163], v[96:99], v[0:15]
	ds_read_b64_tr_b16 v[152:153], v177 offset:6144
	ds_read_b64_tr_b16 v[154:155], v177 offset:7168
	v_add_f32_e32 v131, v131, v83
	v_cvt_pk_bf16_f32 v121, v82, v83
	v_exp_f32_e32 v84, v84
	v_exp_f32_e32 v85, v85
	s_waitcnt lgkmcnt(10)
	v_mfma_f32_32x32x16_bf16 v[16:31], v[164:167], v[96:99], v[16:31]
	ds_read_b64_tr_b16 v[156:157], v177 offset:6656
	ds_read_b64_tr_b16 v[158:159], v177 offset:7680
	v_add_f32_e32 v130, v130, v84
	v_add_f32_e32 v131, v131, v85
	v_cvt_pk_bf16_f32 v122, v84, v85
	v_exp_f32_e32 v86, v86
	s_waitcnt lgkmcnt(10)
	v_mfma_f32_32x32x16_bf16 v[0:15], v[168:171], v[100:103], v[0:15]
	ds_read_b128 v[160:163], v141 offset:13312
	v_exp_f32_e32 v87, v87
	v_add_f32_e32 v130, v130, v86
	v_add_f32_e32 v131, v131, v87
	v_cvt_pk_bf16_f32 v123, v86, v87
	s_waitcnt lgkmcnt(9)
	v_mfma_f32_32x32x16_bf16 v[16:31], v[172:175], v[100:103], v[16:31]
	ds_read_b128 v[164:167], v141 offset:13344
	v_exp_f32_e32 v88, v88
	v_exp_f32_e32 v89, v89
	v_add_f32_e32 v130, v130, v88
	v_add_f32_e32 v131, v131, v89
	s_waitcnt lgkmcnt(8)
	v_mfma_f32_32x32x16_bf16 v[0:15], v[144:147], v[104:107], v[0:15]
	ds_read_b128 v[168:171], v141 offset:13376
	v_cvt_pk_bf16_f32 v124, v88, v89
	v_exp_f32_e32 v90, v90
	v_exp_f32_e32 v91, v91
	v_add_f32_e32 v130, v130, v90
	s_waitcnt lgkmcnt(7)
	v_mfma_f32_32x32x16_bf16 v[16:31], v[148:151], v[104:107], v[16:31]
	ds_read_b128 v[172:175], v141 offset:13408
	v_add_f32_e32 v131, v131, v91
	v_cvt_pk_bf16_f32 v125, v90, v91
	v_exp_f32_e32 v92, v92
	v_exp_f32_e32 v93, v93
	s_waitcnt lgkmcnt(6)
	v_mfma_f32_32x32x16_bf16 v[0:15], v[152:155], v[108:111], v[0:15]
	ds_read_b128 v[144:147], v141 offset:13440
	v_add_f32_e32 v130, v130, v92
	v_add_f32_e32 v131, v131, v93
	v_cvt_pk_bf16_f32 v126, v92, v93
	v_exp_f32_e32 v94, v94
	s_waitcnt lgkmcnt(5)
	v_mfma_f32_32x32x16_bf16 v[16:31], v[156:159], v[108:111], v[16:31]
	ds_read_b128 v[148:151], v141 offset:13472
	v_exp_f32_e32 v95, v95
	v_add_f32_e32 v130, v130, v94
	v_add_f32_e32 v131, v131, v95
	v_cvt_pk_bf16_f32 v127, v94, v95
	s_mov_b32 s0, s64
	s_mov_b32 s64, s65
	s_mov_b32 s65, s68
	s_mov_b32 s68, s0
	s_mov_b32 s0, s69
	s_mov_b32 s69, s70
	s_mov_b32 s70, s71
	s_mov_b32 s71, s0
	s_add_i32 s27, s27, -1
	s_barrier
	s_cmp_lg_u32 s27, 0
	s_cbranch_scc1 .Lat_m_loop
.Lat_m_last:
	v_add_u32_e32 v140, s64, v237
	v_add_u32_e32 v141, s65, v237
	v_add_u32_e32 v176, s69, v238
	v_add_u32_e32 v177, s70, v238
	s_waitcnt lgkmcnt(5)
	v_mfma_f32_32x32x16_bf16 v[64:79], v[160:163], v[184:187], 0
	ds_read_b128 v[152:155], v140 offset:19968
	v_exp_f32_e32 v32, v32
	v_exp_f32_e32 v33, v33
	v_add_f32_e32 v130, v130, v32
	v_add_f32_e32 v131, v131, v33
	s_waitcnt lgkmcnt(5)
	v_mfma_f32_32x32x16_bf16 v[64:79], v[164:167], v[188:191], v[64:79]
	ds_read_b128 v[156:159], v140 offset:20000
	v_cvt_pk_bf16_f32 v96, v32, v33
	v_exp_f32_e32 v34, v34
	v_exp_f32_e32 v35, v35
	v_add_f32_e32 v130, v130, v34
	s_waitcnt lgkmcnt(5)
	v_mfma_f32_32x32x16_bf16 v[64:79], v[168:171], v[192:195], v[64:79]
	ds_read_b128 v[160:163], v140 offset:20032
	v_add_f32_e32 v131, v131, v35
	v_cvt_pk_bf16_f32 v97, v34, v35
	v_exp_f32_e32 v36, v36
	v_exp_f32_e32 v37, v37
	s_waitcnt lgkmcnt(5)
	v_mfma_f32_32x32x16_bf16 v[64:79], v[172:175], v[196:199], v[64:79]
	ds_read_b128 v[164:167], v140 offset:20064
	v_add_f32_e32 v130, v130, v36
	v_add_f32_e32 v131, v131, v37
	v_cvt_pk_bf16_f32 v98, v36, v37
	v_exp_f32_e32 v38, v38
	s_waitcnt lgkmcnt(5)
	v_mfma_f32_32x32x16_bf16 v[64:79], v[144:147], v[200:203], v[64:79]
	ds_read_b128 v[168:171], v140 offset:20096
	v_exp_f32_e32 v39, v39
	v_add_f32_e32 v130, v130, v38
	v_add_f32_e32 v131, v131, v39
	v_cvt_pk_bf16_f32 v99, v38, v39
	s_waitcnt lgkmcnt(5)
	v_mfma_f32_32x32x16_bf16 v[64:79], v[148:151], v[204:207], v[64:79]
	ds_read_b128 v[172:175], v140 offset:20128
	v_exp_f32_e32 v40, v40
	v_exp_f32_e32 v41, v41
	v_add_f32_e32 v130, v130, v40
	v_add_f32_e32 v131, v131, v41
	s_waitcnt lgkmcnt(5)
	v_mfma_f32_32x32x16_bf16 v[80:95], v[152:155], v[184:187], 0
	ds_read_b64_tr_b16 v[144:145], v176 offset:8192
	ds_read_b64_tr_b16 v[146:147], v176 offset:9216
	v_cvt_pk_bf16_f32 v100, v40, v41
	v_exp_f32_e32 v42, v42
	v_exp_f32_e32 v43, v43
	v_add_f32_e32 v130, v130, v42
	s_waitcnt lgkmcnt(6)
	v_mfma_f32_32x32x16_bf16 v[80:95], v[156:159], v[188:191], v[80:95]
	ds_read_b64_tr_b16 v[148:149], v176 offset:8704
	ds_read_b64_tr_b16 v[150:151], v176 offset:9728
	v_add_f32_e32 v131, v131, v43
	v_cvt_pk_bf16_f32 v101, v42, v43
	v_exp_f32_e32 v44, v44
	v_exp_f32_e32 v45, v45
	s_waitcnt lgkmcnt(7)
	v_mfma_f32_32x32x16_bf16 v[80:95], v[160:163], v[192:195], v[80:95]
	ds_read_b64_tr_b16 v[152:153], v176 offset:10240
	ds_read_b64_tr_b16 v[154:155], v176 offset:11264
	v_add_f32_e32 v130, v130, v44
	v_add_f32_e32 v131, v131, v45
	v_cvt_pk_bf16_f32 v102, v44, v45
	v_exp_f32_e32 v46, v46
	s_waitcnt lgkmcnt(8)
	v_mfma_f32_32x32x16_bf16 v[80:95], v[164:167], v[196:199], v[80:95]
	ds_read_b64_tr_b16 v[156:157], v176 offset:10752
	ds_read_b64_tr_b16 v[158:159], v176 offset:11776
	v_exp_f32_e32 v47, v47
	v_add_f32_e32 v130, v130, v46
	v_add_f32_e32 v131, v131, v47
	v_cvt_pk_bf16_f32 v103, v46, v47
	s_waitcnt lgkmcnt(9)
	v_mfma_f32_32x32x16_bf16 v[80:95], v[168:171], v[200:203], v[80:95]
	ds_read_b64_tr_b16 v[160:161], v176 offset:12288
	ds_read_b64_tr_b16 v[162:163], v176 offset:13312
	v_exp_f32_e32 v48, v48
	v_exp_f32_e32 v49, v49
	v_add_f32_e32 v130, v130, v48
	v_add_f32_e32 v131, v131, v49
	s_waitcnt lgkmcnt(10)
	v_mfma_f32_32x32x16_bf16 v[80:95], v[172:175], v[204:207], v[80:95]
	ds_read_b64_tr_b16 v[164:165], v176 offset:12800
	ds_read_b64_tr_b16 v[166:167], v176 offset:13824
	v_cvt_pk_bf16_f32 v104, v48, v49
	v_exp_f32_e32 v50, v50
	v_exp_f32_e32 v51, v51
	v_add_f32_e32 v130, v130, v50
	s_waitcnt lgkmcnt(10)
	v_mfma_f32_32x32x16_bf16 v[0:15], v[144:147], v[112:115], v[0:15]
	ds_read_b64_tr_b16 v[168:169], v176 offset:14336
	ds_read_b64_tr_b16 v[170:171], v176 offset:15360
	v_add_f32_e32 v131, v131, v51
	v_cvt_pk_bf16_f32 v105, v50, v51
	v_exp_f32_e32 v52, v52
	v_exp_f32_e32 v53, v53
	s_waitcnt lgkmcnt(10)
	v_mfma_f32_32x32x16_bf16 v[16:31], v[148:151], v[112:115], v[16:31]
	ds_read_b64_tr_b16 v[172:173], v176 offset:14848
	ds_read_b64_tr_b16 v[174:175], v176 offset:15872
	v_add_f32_e32 v130, v130, v52
	v_add_f32_e32 v131, v131, v53
	v_cvt_pk_bf16_f32 v106, v52, v53
	v_exp_f32_e32 v54, v54
	s_waitcnt lgkmcnt(10)
	v_mfma_f32_32x32x16_bf16 v[0:15], v[152:155], v[116:119], v[0:15]
	ds_read_b64_tr_b16 v[144:145], v177 offset:0
	ds_read_b64_tr_b16 v[146:147], v177 offset:1024
	v_exp_f32_e32 v55, v55
	v_add_f32_e32 v130, v130, v54
	v_add_f32_e32 v131, v131, v55
	v_cvt_pk_bf16_f32 v107, v54, v55
	s_waitcnt lgkmcnt(10)
	v_mfma_f32_32x32x16_bf16 v[16:31], v[156:159], v[116:119], v[16:31]
	ds_read_b64_tr_b16 v[148:149], v177 offset:512
	ds_read_b64_tr_b16 v[150:151], v177 offset:1536
	v_exp_f32_e32 v56, v56
	v_exp_f32_e32 v57, v57
	v_add_f32_e32 v130, v130, v56
	v_add_f32_e32 v131, v131, v57
	s_waitcnt lgkmcnt(10)
	v_mfma_f32_32x32x16_bf16 v[0:15], v[160:163], v[120:123], v[0:15]
	ds_read_b64_tr_b16 v[152:153], v177 offset:2048
	ds_read_b64_tr_b16 v[154:155], v177 offset:3072
	v_cvt_pk_bf16_f32 v108, v56, v57
	v_exp_f32_e32 v58, v58
	v_exp_f32_e32 v59, v59
	v_add_f32_e32 v130, v130, v58
	s_waitcnt lgkmcnt(10)
	v_mfma_f32_32x32x16_bf16 v[16:31], v[164:167], v[120:123], v[16:31]
	ds_read_b64_tr_b16 v[156:157], v177 offset:2560
	ds_read_b64_tr_b16 v[158:159], v177 offset:3584
	v_add_f32_e32 v131, v131, v59
	v_cvt_pk_bf16_f32 v109, v58, v59
	v_exp_f32_e32 v60, v60
	v_exp_f32_e32 v61, v61
	s_waitcnt lgkmcnt(10)
	v_mfma_f32_32x32x16_bf16 v[0:15], v[168:171], v[124:127], v[0:15]
	ds_read_b64_tr_b16 v[160:161], v177 offset:4096
	ds_read_b64_tr_b16 v[162:163], v177 offset:5120
	v_add_f32_e32 v130, v130, v60
	v_add_f32_e32 v131, v131, v61
	v_cvt_pk_bf16_f32 v110, v60, v61
	v_exp_f32_e32 v62, v62
	s_waitcnt lgkmcnt(10)
	v_mfma_f32_32x32x16_bf16 v[16:31], v[172:175], v[124:127], v[16:31]
	ds_read_b64_tr_b16 v[164:165], v177 offset:4608
	ds_read_b64_tr_b16 v[166:167], v177 offset:5632
	v_exp_f32_e32 v63, v63
	v_add_f32_e32 v130, v130, v62
	v_add_f32_e32 v131, v131, v63
	v_cvt_pk_bf16_f32 v111, v62, v63
	s_waitcnt lgkmcnt(10)
	v_mfma_f32_32x32x16_bf16 v[0:15], v[144:147], v[96:99], v[0:15]
	ds_read_b64_tr_b16 v[168:169], v177 offset:6144
	ds_read_b64_tr_b16 v[170:171], v177 offset:7168
	v_exp_f32_e32 v64, v64
	v_exp_f32_e32 v65, v65
	v_add_f32_e32 v130, v130, v64
	v_add_f32_e32 v131, v131, v65
	v_cvt_pk_bf16_f32 v112, v64, v65
	v_exp_f32_e32 v66, v66
	v_exp_f32_e32 v67, v67
	v_add_f32_e32 v130, v130, v66
	v_add_f32_e32 v131, v131, v67
	v_cvt_pk_bf16_f32 v113, v66, v67
	s_waitcnt lgkmcnt(10)
	v_mfma_f32_32x32x16_bf16 v[16:31], v[148:151], v[96:99], v[16:31]
	ds_read_b64_tr_b16 v[172:173], v177 offset:6656
	ds_read_b64_tr_b16 v[174:175], v177 offset:7680
	v_exp_f32_e32 v68, v68
	v_exp_f32_e32 v69, v69
	v_add_f32_e32 v130, v130, v68
	v_add_f32_e32 v131, v131, v69
	v_cvt_pk_bf16_f32 v114, v68, v69
	v_exp_f32_e32 v70, v70
	v_exp_f32_e32 v71, v71
	v_add_f32_e32 v130, v130, v70
	v_add_f32_e32 v131, v131, v71
	v_cvt_pk_bf16_f32 v115, v70, v71
	s_waitcnt lgkmcnt(10)
	v_mfma_f32_32x32x16_bf16 v[0:15], v[152:155], v[100:103], v[0:15]
	v_exp_f32_e32 v72, v72
	v_exp_f32_e32 v73, v73
	v_add_f32_e32 v130, v130, v72
	v_add_f32_e32 v131, v131, v73
	v_cvt_pk_bf16_f32 v116, v72, v73
	v_exp_f32_e32 v74, v74
	v_exp_f32_e32 v75, v75
	v_add_f32_e32 v130, v130, v74
	v_add_f32_e32 v131, v131, v75
	v_cvt_pk_bf16_f32 v117, v74, v75
	s_waitcnt lgkmcnt(8)
	v_mfma_f32_32x32x16_bf16 v[16:31], v[156:159], v[100:103], v[16:31]
	v_exp_f32_e32 v76, v76
	v_exp_f32_e32 v77, v77
	v_add_f32_e32 v130, v130, v76
	v_add_f32_e32 v131, v131, v77
	v_cvt_pk_bf16_f32 v118, v76, v77
	v_exp_f32_e32 v78, v78
	v_exp_f32_e32 v79, v79
	v_add_f32_e32 v130, v130, v78
	v_add_f32_e32 v131, v131, v79
	v_cvt_pk_bf16_f32 v119, v78, v79
	s_waitcnt lgkmcnt(6)
	v_mfma_f32_32x32x16_bf16 v[0:15], v[160:163], v[104:107], v[0:15]
	v_exp_f32_e32 v80, v80
	v_exp_f32_e32 v81, v81
	v_add_f32_e32 v130, v130, v80
	v_add_f32_e32 v131, v131, v81
	v_cvt_pk_bf16_f32 v120, v80, v81
	v_exp_f32_e32 v82, v82
	v_exp_f32_e32 v83, v83
	v_add_f32_e32 v130, v130, v82
	v_add_f32_e32 v131, v131, v83
	v_cvt_pk_bf16_f32 v121, v82, v83
	s_waitcnt lgkmcnt(4)
	v_mfma_f32_32x32x16_bf16 v[16:31], v[164:167], v[104:107], v[16:31]
	v_exp_f32_e32 v84, v84
	v_exp_f32_e32 v85, v85
	v_add_f32_e32 v130, v130, v84
	v_add_f32_e32 v131, v131, v85
	v_cvt_pk_bf16_f32 v122, v84, v85
	v_exp_f32_e32 v86, v86
	v_exp_f32_e32 v87, v87
	v_add_f32_e32 v130, v130, v86
	v_add_f32_e32 v131, v131, v87
	v_cvt_pk_bf16_f32 v123, v86, v87
	s_waitcnt lgkmcnt(2)
	v_mfma_f32_32x32x16_bf16 v[0:15], v[168:171], v[108:111], v[0:15]
	v_exp_f32_e32 v88, v88
	v_exp_f32_e32 v89, v89
	v_add_f32_e32 v130, v130, v88
	v_add_f32_e32 v131, v131, v89
	v_cvt_pk_bf16_f32 v124, v88, v89
	v_exp_f32_e32 v90, v90
	v_exp_f32_e32 v91, v91
	v_add_f32_e32 v130, v130, v90
	v_add_f32_e32 v131, v131, v91
	v_cvt_pk_bf16_f32 v125, v90, v91
	s_waitcnt lgkmcnt(0)
	v_mfma_f32_32x32x16_bf16 v[16:31], v[172:175], v[108:111], v[16:31]
	v_exp_f32_e32 v92, v92
	v_exp_f32_e32 v93, v93
	v_add_f32_e32 v130, v130, v92
	v_add_f32_e32 v131, v131, v93
	v_cvt_pk_bf16_f32 v126, v92, v93
	v_exp_f32_e32 v94, v94
	v_exp_f32_e32 v95, v95
	v_add_f32_e32 v130, v130, v94
	v_add_f32_e32 v131, v131, v95
	v_cvt_pk_bf16_f32 v127, v94, v95
	v_add_u32_e32 v176, s70, v238
	ds_read_b64_tr_b16 v[144:145], v176 offset:8192
	ds_read_b64_tr_b16 v[146:147], v176 offset:9216
	ds_read_b64_tr_b16 v[148:149], v176 offset:8704
	ds_read_b64_tr_b16 v[150:151], v176 offset:9728
	ds_read_b64_tr_b16 v[152:153], v176 offset:10240
	ds_read_b64_tr_b16 v[154:155], v176 offset:11264
	ds_read_b64_tr_b16 v[156:157], v176 offset:10752
	ds_read_b64_tr_b16 v[158:159], v176 offset:11776
	ds_read_b64_tr_b16 v[160:161], v176 offset:12288
	ds_read_b64_tr_b16 v[162:163], v176 offset:13312
	ds_read_b64_tr_b16 v[164:165], v176 offset:12800
	ds_read_b64_tr_b16 v[166:167], v176 offset:13824
	s_waitcnt lgkmcnt(10)
	v_mfma_f32_32x32x16_bf16 v[0:15], v[144:147], v[112:115], v[0:15]
	ds_read_b64_tr_b16 v[168:169], v176 offset:14336
	ds_read_b64_tr_b16 v[170:171], v176 offset:15360
	s_waitcnt lgkmcnt(10)
	v_mfma_f32_32x32x16_bf16 v[16:31], v[148:151], v[112:115], v[16:31]
	ds_read_b64_tr_b16 v[172:173], v176 offset:14848
	ds_read_b64_tr_b16 v[174:175], v176 offset:15872
	s_waitcnt lgkmcnt(10)
	v_mfma_f32_32x32x16_bf16 v[0:15], v[152:155], v[116:119], v[0:15]
	s_waitcnt lgkmcnt(8)
	v_mfma_f32_32x32x16_bf16 v[16:31], v[156:159], v[116:119], v[16:31]
	s_waitcnt lgkmcnt(6)
	v_mfma_f32_32x32x16_bf16 v[0:15], v[160:163], v[120:123], v[0:15]
	s_waitcnt lgkmcnt(4)
	v_mfma_f32_32x32x16_bf16 v[16:31], v[164:167], v[120:123], v[16:31]
	s_waitcnt lgkmcnt(2)
	v_mfma_f32_32x32x16_bf16 v[0:15], v[168:171], v[124:127], v[0:15]
	s_waitcnt lgkmcnt(0)
	v_mfma_f32_32x32x16_bf16 v[16:31], v[172:175], v[124:127], v[16:31]
	global_load_dwordx2 v[32:33], v133, s[12:13] offset:0
	global_load_dwordx2 v[34:35], v133, s[12:13] offset:64
	global_load_dwordx2 v[36:37], v133, s[12:13] offset:16
	global_load_dwordx2 v[38:39], v133, s[12:13] offset:80
	global_load_dwordx2 v[40:41], v133, s[12:13] offset:32
	global_load_dwordx2 v[42:43], v133, s[12:13] offset:96
	global_load_dwordx2 v[44:45], v133, s[12:13] offset:48
	global_load_dwordx2 v[46:47], v133, s[12:13] offset:112
	v_add_f32_e32 v135, v130, v131
	v_mov_b32_e32 v128, v135
	s_nop 1
	v_permlane32_swap_b32_e32 v135, v128
	s_nop 1
	v_add_f32_e32 v135, v135, v128
	s_mov_b32 s0, 0x7149f2ca
	v_cmp_lt_f32_e32 vcc, 0xda24260, v135
	v_cmp_gt_f32_e64 s[76:77], s0, v135
	s_nop 1
	s_and_b64 s[76:77], s[76:77], vcc
	s_andn2_b64 s[76:77], exec, s[76:77]
	s_cmp_lg_u64 s[76:77], 0
	s_cselect_b32 s0, 1, 0
	v_mov_b32_e32 v128, s0
	v_lshrrev_b32_e32 v132, 6, v143
	v_lshlrev_b32_e32 v132, 2, v132
	v_add_u32_e32 v132, 131072, v132
	ds_write_b32 v132, v128
	s_waitcnt lgkmcnt(0)
	s_barrier
	v_mov_b32_e32 v132, 131072
	ds_read_b128 v[48:51], v132
	ds_read_b128 v[52:55], v132 offset:16
	v_rcp_f32_e32 v136, v135
	s_nop 0
	v_fma_f32 v128, -v135, v136, 1.0
	v_fma_f32 v136, v136, v128, v136
	s_waitcnt lgkmcnt(0)
	v_or_b32_e32 v48, v48, v49
	v_or3_b32 v48, v48, v50, v51
	v_or3_b32 v48, v48, v52, v53
	v_or3_b32 v48, v48, v54, v55
	s_nop 0
	v_readfirstlane_b32 s0, v48
	s_and_b32 s1, s9, 31
	s_lshl_b32 s1, 1, s1
	s_cmp_lg_u32 s0, 0
	s_cselect_b32 s1, s1, 0
	s_or_b32 s26, s26, s1
	s_waitcnt vmcnt(0)
	s_mov_b32 s0, 0xbfb8aa3b
	v_lshlrev_b32_e32 v56, 16, v32
	v_and_b32_e32 v57, 0xffff0000, v32
	v_lshlrev_b32_e32 v58, 16, v33
	v_and_b32_e32 v59, 0xffff0000, v33
	v_mul_f32_e32 v62, s0, v56
	v_mul_f32_e32 v63, s0, v57
	v_mul_f32_e32 v48, s0, v58
	v_mul_f32_e32 v49, s0, v59
	v_exp_f32_e32 v62, v62
	v_exp_f32_e32 v63, v63
	v_exp_f32_e32 v48, v48
	v_exp_f32_e32 v49, v49
	s_nop 0
	v_add_f32_e32 v62, 1.0, v62
	v_add_f32_e32 v63, 1.0, v63
	v_add_f32_e32 v48, 1.0, v48
	v_add_f32_e32 v49, 1.0, v49
	v_rcp_f32_e32 v62, v62
	v_rcp_f32_e32 v63, v63
	v_rcp_f32_e32 v48, v48
	v_rcp_f32_e32 v49, v49
	s_nop 0
	v_mul_f32_e32 v56, v56, v62
	v_mul_f32_e32 v57, v57, v63
	v_mul_f32_e32 v58, v58, v48
	v_mul_f32_e32 v59, v59, v49
	v_mul_f32_e32 v62, v0, v136
	v_mul_f32_e32 v63, v1, v136
	v_mul_f32_e32 v48, v2, v136
	v_mul_f32_e32 v49, v3, v136
	v_mul_f32_e32 v62, v62, v56
	v_mul_f32_e32 v63, v63, v57
	v_mul_f32_e32 v48, v48, v58
	v_mul_f32_e32 v49, v49, v59
	v_cvt_pk_bf16_f32 v60, v62, v63
	v_cvt_pk_bf16_f32 v61, v48, v49
	global_store_dwordx2 v134, v[60:61], s[14:15] offset:0
	s_nop 0
	v_lshlrev_b32_e32 v56, 16, v34
	v_and_b32_e32 v57, 0xffff0000, v34
	v_lshlrev_b32_e32 v58, 16, v35
	v_and_b32_e32 v59, 0xffff0000, v35
	v_mul_f32_e32 v62, s0, v56
	v_mul_f32_e32 v63, s0, v57
	v_mul_f32_e32 v48, s0, v58
	v_mul_f32_e32 v49, s0, v59
	v_exp_f32_e32 v62, v62
	v_exp_f32_e32 v63, v63
	v_exp_f32_e32 v48, v48
	v_exp_f32_e32 v49, v49
	s_nop 0
	v_add_f32_e32 v62, 1.0, v62
	v_add_f32_e32 v63, 1.0, v63
	v_add_f32_e32 v48, 1.0, v48
	v_add_f32_e32 v49, 1.0, v49
	v_rcp_f32_e32 v62, v62
	v_rcp_f32_e32 v63, v63
	v_rcp_f32_e32 v48, v48
	v_rcp_f32_e32 v49, v49
	s_nop 0
	v_mul_f32_e32 v56, v56, v62
	v_mul_f32_e32 v57, v57, v63
	v_mul_f32_e32 v58, v58, v48
	v_mul_f32_e32 v59, v59, v49
	v_mul_f32_e32 v62, v16, v136
	v_mul_f32_e32 v63, v17, v136
	v_mul_f32_e32 v48, v18, v136
	v_mul_f32_e32 v49, v19, v136
	v_mul_f32_e32 v62, v62, v56
	v_mul_f32_e32 v63, v63, v57
	v_mul_f32_e32 v48, v48, v58
	v_mul_f32_e32 v49, v49, v59
	v_cvt_pk_bf16_f32 v60, v62, v63
	v_cvt_pk_bf16_f32 v61, v48, v49
	global_store_dwordx2 v134, v[60:61], s[14:15] offset:64
	s_nop 0
	v_lshlrev_b32_e32 v56, 16, v36
	v_and_b32_e32 v57, 0xffff0000, v36
	v_lshlrev_b32_e32 v58, 16, v37
	v_and_b32_e32 v59, 0xffff0000, v37
	v_mul_f32_e32 v62, s0, v56
	v_mul_f32_e32 v63, s0, v57
	v_mul_f32_e32 v48, s0, v58
	v_mul_f32_e32 v49, s0, v59
	v_exp_f32_e32 v62, v62
	v_exp_f32_e32 v63, v63
	v_exp_f32_e32 v48, v48
	v_exp_f32_e32 v49, v49
	s_nop 0
	v_add_f32_e32 v62, 1.0, v62
	v_add_f32_e32 v63, 1.0, v63
	v_add_f32_e32 v48, 1.0, v48
	v_add_f32_e32 v49, 1.0, v49
	v_rcp_f32_e32 v62, v62
	v_rcp_f32_e32 v63, v63
	v_rcp_f32_e32 v48, v48
	v_rcp_f32_e32 v49, v49
	s_nop 0
	v_mul_f32_e32 v56, v56, v62
	v_mul_f32_e32 v57, v57, v63
	v_mul_f32_e32 v58, v58, v48
	v_mul_f32_e32 v59, v59, v49
	v_mul_f32_e32 v62, v4, v136
	v_mul_f32_e32 v63, v5, v136
	v_mul_f32_e32 v48, v6, v136
	v_mul_f32_e32 v49, v7, v136
	v_mul_f32_e32 v62, v62, v56
	v_mul_f32_e32 v63, v63, v57
	v_mul_f32_e32 v48, v48, v58
	v_mul_f32_e32 v49, v49, v59
	v_cvt_pk_bf16_f32 v60, v62, v63
	v_cvt_pk_bf16_f32 v61, v48, v49
	global_store_dwordx2 v134, v[60:61], s[14:15] offset:16
	s_nop 0
	v_lshlrev_b32_e32 v56, 16, v38
	v_and_b32_e32 v57, 0xffff0000, v38
	v_lshlrev_b32_e32 v58, 16, v39
	v_and_b32_e32 v59, 0xffff0000, v39
	v_mul_f32_e32 v62, s0, v56
	v_mul_f32_e32 v63, s0, v57
	v_mul_f32_e32 v48, s0, v58
	v_mul_f32_e32 v49, s0, v59
	v_exp_f32_e32 v62, v62
	v_exp_f32_e32 v63, v63
	v_exp_f32_e32 v48, v48
	v_exp_f32_e32 v49, v49
	s_nop 0
	v_add_f32_e32 v62, 1.0, v62
	v_add_f32_e32 v63, 1.0, v63
	v_add_f32_e32 v48, 1.0, v48
	v_add_f32_e32 v49, 1.0, v49
	v_rcp_f32_e32 v62, v62
	v_rcp_f32_e32 v63, v63
	v_rcp_f32_e32 v48, v48
	v_rcp_f32_e32 v49, v49
	s_nop 0
	v_mul_f32_e32 v56, v56, v62
	v_mul_f32_e32 v57, v57, v63
	v_mul_f32_e32 v58, v58, v48
	v_mul_f32_e32 v59, v59, v49
	v_mul_f32_e32 v62, v20, v136
	v_mul_f32_e32 v63, v21, v136
	v_mul_f32_e32 v48, v22, v136
	v_mul_f32_e32 v49, v23, v136
	v_mul_f32_e32 v62, v62, v56
	v_mul_f32_e32 v63, v63, v57
	v_mul_f32_e32 v48, v48, v58
	v_mul_f32_e32 v49, v49, v59
	v_cvt_pk_bf16_f32 v60, v62, v63
	v_cvt_pk_bf16_f32 v61, v48, v49
	global_store_dwordx2 v134, v[60:61], s[14:15] offset:80
	s_nop 0
	v_lshlrev_b32_e32 v56, 16, v40
	v_and_b32_e32 v57, 0xffff0000, v40
	v_lshlrev_b32_e32 v58, 16, v41
	v_and_b32_e32 v59, 0xffff0000, v41
	v_mul_f32_e32 v62, s0, v56
	v_mul_f32_e32 v63, s0, v57
	v_mul_f32_e32 v48, s0, v58
	v_mul_f32_e32 v49, s0, v59
	v_exp_f32_e32 v62, v62
	v_exp_f32_e32 v63, v63
	v_exp_f32_e32 v48, v48
	v_exp_f32_e32 v49, v49
	s_nop 0
	v_add_f32_e32 v62, 1.0, v62
	v_add_f32_e32 v63, 1.0, v63
	v_add_f32_e32 v48, 1.0, v48
	v_add_f32_e32 v49, 1.0, v49
	v_rcp_f32_e32 v62, v62
	v_rcp_f32_e32 v63, v63
	v_rcp_f32_e32 v48, v48
	v_rcp_f32_e32 v49, v49
	s_nop 0
	v_mul_f32_e32 v56, v56, v62
	v_mul_f32_e32 v57, v57, v63
	v_mul_f32_e32 v58, v58, v48
	v_mul_f32_e32 v59, v59, v49
	v_mul_f32_e32 v62, v8, v136
	v_mul_f32_e32 v63, v9, v136
	v_mul_f32_e32 v48, v10, v136
	v_mul_f32_e32 v49, v11, v136
	v_mul_f32_e32 v62, v62, v56
	v_mul_f32_e32 v63, v63, v57
	v_mul_f32_e32 v48, v48, v58
	v_mul_f32_e32 v49, v49, v59
	v_cvt_pk_bf16_f32 v60, v62, v63
	v_cvt_pk_bf16_f32 v61, v48, v49
	global_store_dwordx2 v134, v[60:61], s[14:15] offset:32
	s_nop 0
	v_lshlrev_b32_e32 v56, 16, v42
	v_and_b32_e32 v57, 0xffff0000, v42
	v_lshlrev_b32_e32 v58, 16, v43
	v_and_b32_e32 v59, 0xffff0000, v43
	v_mul_f32_e32 v62, s0, v56
	v_mul_f32_e32 v63, s0, v57
	v_mul_f32_e32 v48, s0, v58
	v_mul_f32_e32 v49, s0, v59
	v_exp_f32_e32 v62, v62
	v_exp_f32_e32 v63, v63
	v_exp_f32_e32 v48, v48
	v_exp_f32_e32 v49, v49
	s_nop 0
	v_add_f32_e32 v62, 1.0, v62
	v_add_f32_e32 v63, 1.0, v63
	v_add_f32_e32 v48, 1.0, v48
	v_add_f32_e32 v49, 1.0, v49
	v_rcp_f32_e32 v62, v62
	v_rcp_f32_e32 v63, v63
	v_rcp_f32_e32 v48, v48
	v_rcp_f32_e32 v49, v49
	s_nop 0
	v_mul_f32_e32 v56, v56, v62
	v_mul_f32_e32 v57, v57, v63
	v_mul_f32_e32 v58, v58, v48
	v_mul_f32_e32 v59, v59, v49
	v_mul_f32_e32 v62, v24, v136
	v_mul_f32_e32 v63, v25, v136
	v_mul_f32_e32 v48, v26, v136
	v_mul_f32_e32 v49, v27, v136
	v_mul_f32_e32 v62, v62, v56
	v_mul_f32_e32 v63, v63, v57
	v_mul_f32_e32 v48, v48, v58
	v_mul_f32_e32 v49, v49, v59
	v_cvt_pk_bf16_f32 v60, v62, v63
	v_cvt_pk_bf16_f32 v61, v48, v49
	global_store_dwordx2 v134, v[60:61], s[14:15] offset:96
	s_nop 0
	v_lshlrev_b32_e32 v56, 16, v44
	v_and_b32_e32 v57, 0xffff0000, v44
	v_lshlrev_b32_e32 v58, 16, v45
	v_and_b32_e32 v59, 0xffff0000, v45
	v_mul_f32_e32 v62, s0, v56
	v_mul_f32_e32 v63, s0, v57
	v_mul_f32_e32 v48, s0, v58
	v_mul_f32_e32 v49, s0, v59
	v_exp_f32_e32 v62, v62
	v_exp_f32_e32 v63, v63
	v_exp_f32_e32 v48, v48
	v_exp_f32_e32 v49, v49
	s_nop 0
	v_add_f32_e32 v62, 1.0, v62
	v_add_f32_e32 v63, 1.0, v63
	v_add_f32_e32 v48, 1.0, v48
	v_add_f32_e32 v49, 1.0, v49
	v_rcp_f32_e32 v62, v62
	v_rcp_f32_e32 v63, v63
	v_rcp_f32_e32 v48, v48
	v_rcp_f32_e32 v49, v49
	s_nop 0
	v_mul_f32_e32 v56, v56, v62
	v_mul_f32_e32 v57, v57, v63
	v_mul_f32_e32 v58, v58, v48
	v_mul_f32_e32 v59, v59, v49
	v_mul_f32_e32 v62, v12, v136
	v_mul_f32_e32 v63, v13, v136
	v_mul_f32_e32 v48, v14, v136
	v_mul_f32_e32 v49, v15, v136
	v_mul_f32_e32 v62, v62, v56
	v_mul_f32_e32 v63, v63, v57
	v_mul_f32_e32 v48, v48, v58
	v_mul_f32_e32 v49, v49, v59
	v_cvt_pk_bf16_f32 v60, v62, v63
	v_cvt_pk_bf16_f32 v61, v48, v49
	global_store_dwordx2 v134, v[60:61], s[14:15] offset:48
	s_nop 0
	v_lshlrev_b32_e32 v56, 16, v46
	v_and_b32_e32 v57, 0xffff0000, v46
	v_lshlrev_b32_e32 v58, 16, v47
	v_and_b32_e32 v59, 0xffff0000, v47
	v_mul_f32_e32 v62, s0, v56
	v_mul_f32_e32 v63, s0, v57
	v_mul_f32_e32 v48, s0, v58
	v_mul_f32_e32 v49, s0, v59
	v_exp_f32_e32 v62, v62
	v_exp_f32_e32 v63, v63
	v_exp_f32_e32 v48, v48
	v_exp_f32_e32 v49, v49
	s_nop 0
	v_add_f32_e32 v62, 1.0, v62
	v_add_f32_e32 v63, 1.0, v63
	v_add_f32_e32 v48, 1.0, v48
	v_add_f32_e32 v49, 1.0, v49
	v_rcp_f32_e32 v62, v62
	v_rcp_f32_e32 v63, v63
	v_rcp_f32_e32 v48, v48
	v_rcp_f32_e32 v49, v49
	s_nop 0
	v_mul_f32_e32 v56, v56, v62
	v_mul_f32_e32 v57, v57, v63
	v_mul_f32_e32 v58, v58, v48
	v_mul_f32_e32 v59, v59, v49
	v_mul_f32_e32 v62, v28, v136
	v_mul_f32_e32 v63, v29, v136
	v_mul_f32_e32 v48, v30, v136
	v_mul_f32_e32 v49, v31, v136
	v_mul_f32_e32 v62, v62, v56
	v_mul_f32_e32 v63, v63, v57
	v_mul_f32_e32 v48, v48, v58
	v_mul_f32_e32 v49, v49, v59
	v_cvt_pk_bf16_f32 v60, v62, v63
	v_cvt_pk_bf16_f32 v61, v48, v49
	global_store_dwordx2 v134, v[60:61], s[14:15] offset:112
	s_nop 0
	s_branch .Lat_next
.Lat_g_unit:
	v_and_b32_e32 v32, 31, v143
	v_bfe_u32 v33, v143, 5, 1
	v_lshrrev_b32_e32 v34, 6, v143
	v_mul_u32_u24_e32 v237, 144, v32
	v_lshl_add_u32 v237, v33, 4, v237
	v_and_b32_e32 v35, 3, v143
	v_lshlrev_b32_e32 v238, 3, v35
	v_bfe_u32 v35, v143, 2, 2
	v_lshl_add_u32 v238, v35, 6, v238
	v_bfe_u32 v35, v143, 4, 1
	v_lshl_add_u32 v238, v35, 5, v238
	v_lshl_add_u32 v238, v33, 8, v238
	v_lshlrev_b32_e32 v232, 4, v143
	v_add_u32_e32 v239, 0x2000, v232
	v_add_u32_e32 v252, 0x4000, v232
	v_mov_b32_e32 v36, v143
	v_lshrrev_b32_e32 v37, 3, v36
	v_and_b32_e32 v38, 7, v36
	v_mul_u32_u24_e32 v37, 144, v37
	v_lshl_add_u32 v179, v38, 4, v37
	v_add_u32_e32 v36, 512, v143
	v_lshrrev_b32_e32 v37, 3, v36
	v_and_b32_e32 v38, 7, v36
	v_mul_u32_u24_e32 v37, 144, v37
	v_lshl_add_u32 v181, v38, 4, v37
	v_lshlrev_b32_e32 v183, 10, v34
	v_bfe_u32 v35, v143, 2, 1
	v_lshl_add_u32 v183, v35, 9, v183
	v_bfe_u32 v35, v143, 3, 3
	v_lshl_add_u32 v183, v35, 6, v183
	v_and_b32_e32 v35, 3, v143
	v_lshl_add_u32 v183, v35, 4, v183
	v_lshl_add_u32 v39, v34, 5, v32
	v_mul_u32_u24_e32 v36, 128, v39
	v_lshl_add_u32 v36, v33, 4, v36
	v_mul_u32_u24_e32 v133, 0x1440, v39
	v_lshl_add_u32 v133, v33, 3, v133
	v_lshlrev_b32_e32 v134, 11, v39
	v_lshl_add_u32 v134, v33, 3, v134
	global_load_dwordx4 v[184:187], v36, s[10:11] offset:0
	global_load_dwordx4 v[188:191], v36, s[10:11] offset:32
	global_load_dwordx4 v[192:195], v36, s[10:11] offset:64
	global_load_dwordx4 v[196:199], v36, s[10:11] offset:96
	global_load_dwordx4 v[208:211], v232, s[16:17]
	global_load_dwordx4 v[212:215], v239, s[16:17]
	global_load_dwordx4 v[220:223], v232, s[22:23]
	global_load_dwordx4 v[224:227], v239, s[22:23]
	s_add_u32 s16, s16, 16384
	s_addc_u32 s17, s17, 0
	s_add_u32 s22, s22, 16384
	s_addc_u32 s23, s23, 0
	global_load_dwordx4 v[144:147], v232, s[16:17]
	global_load_dwordx4 v[148:151], v239, s[16:17]
	s_add_u32 s16, s16, 16384
	s_addc_u32 s17, s17, 0
	s_mov_b32 s64, 0
	s_movk_i32 s65, 18432
	s_mov_b32 s68, 36864
	s_mov_b32 s69, 112640
	s_mov_b32 s70, 79872
	s_mov_b32 s71, 96256
	v_mov_b32_e32 v130, 0
	v_mov_b32_e32 v131, 0
	v_mov_b32_e32 v0, 0
	v_mov_b32_e32 v1, 0
	v_mov_b32_e32 v2, 0
	v_mov_b32_e32 v3, 0
	v_mov_b32_e32 v4, 0
	v_mov_b32_e32 v5, 0
	v_mov_b32_e32 v6, 0
	v_mov_b32_e32 v7, 0
	v_mov_b32_e32 v8, 0
	v_mov_b32_e32 v9, 0
	v_mov_b32_e32 v10, 0
	v_mov_b32_e32 v11, 0
	v_mov_b32_e32 v12, 0
	v_mov_b32_e32 v13, 0
	v_mov_b32_e32 v14, 0
	v_mov_b32_e32 v15, 0
	v_mov_b32_e32 v16, 0
	v_mov_b32_e32 v17, 0
	v_mov_b32_e32 v18, 0
	v_mov_b32_e32 v19, 0
	v_mov_b32_e32 v20, 0
	v_mov_b32_e32 v21, 0
	v_mov_b32_e32 v22, 0
	v_mov_b32_e32 v23, 0
	v_mov_b32_e32 v24, 0
	v_mov_b32_e32 v25, 0
	v_mov_b32_e32 v26, 0
	v_mov_b32_e32 v27, 0
	v_mov_b32_e32 v28, 0
	v_mov_b32_e32 v29, 0
	v_mov_b32_e32 v30, 0
	v_mov_b32_e32 v31, 0
	s_waitcnt vmcnt(2)
	ds_write_b128 v179, v[208:211]
	ds_write_b128 v181, v[212:215]
	v_add_u32_e32 v128, 79872, v183
	ds_write_b128 v128, v[220:223]
	v_add_u32_e32 v128, 79872, v183
	ds_write_b128 v128, v[224:227] offset:8192
	global_load_dwordx4 v[208:211], v232, s[16:17]
	global_load_dwordx4 v[212:215], v239, s[16:17]
	global_load_dwordx4 v[220:223], v232, s[22:23]
	global_load_dwordx4 v[224:227], v239, s[22:23]
	s_add_u32 s16, s16, 16384
	s_addc_u32 s17, s17, 0
	s_add_u32 s22, s22, 16384
	s_addc_u32 s23, s23, 0
	s_waitcnt vmcnt(4)
	v_add_u32_e32 v128, 18432, v179
	ds_write_b128 v128, v[144:147]
	v_add_u32_e32 v128, 18432, v181
	ds_write_b128 v128, v[148:151]
	v_add_u32_e32 v140, s64, v237
	s_waitcnt lgkmcnt(0)
	s_barrier
	ds_read_b128 v[144:147], v140 offset:0
	ds_read_b128 v[148:151], v140 offset:32
	ds_read_b128 v[152:155], v140 offset:64
	ds_read_b128 v[156:159], v140 offset:96
	ds_read_b128 v[160:163], v140 offset:4608
	ds_read_b128 v[164:167], v140 offset:4640
	s_waitcnt lgkmcnt(5)
	v_mfma_f32_32x32x16_bf16 v[32:47], v[144:147], v[184:187], 0
	ds_read_b128 v[168:171], v140 offset:4672
	s_waitcnt lgkmcnt(5)
	v_mfma_f32_32x32x16_bf16 v[32:47], v[148:151], v[188:191], v[32:47]
	ds_read_b128 v[172:175], v140 offset:4704
	s_waitcnt lgkmcnt(5)
	v_mfma_f32_32x32x16_bf16 v[32:47], v[152:155], v[192:195], v[32:47]
	s_waitcnt lgkmcnt(4)
	v_mfma_f32_32x32x16_bf16 v[32:47], v[156:159], v[196:199], v[32:47]
	s_waitcnt lgkmcnt(3)
	v_mfma_f32_32x32x16_bf16 v[48:63], v[160:163], v[184:187], 0
	s_waitcnt lgkmcnt(2)
	v_mfma_f32_32x32x16_bf16 v[48:63], v[164:167], v[188:191], v[48:63]
	s_waitcnt lgkmcnt(1)
	v_mfma_f32_32x32x16_bf16 v[48:63], v[168:171], v[192:195], v[48:63]
	s_waitcnt lgkmcnt(0)
	v_mfma_f32_32x32x16_bf16 v[48:63], v[172:175], v[196:199], v[48:63]
	s_nop 7
	s_nop 3
	v_add_u32_e32 v140, s64, v237
	v_add_u32_e32 v141, s65, v237
	v_add_u32_e32 v176, s69, v238
	v_add_u32_e32 v177, s70, v238
	ds_read_b128 v[144:147], v140 offset:9216
	ds_read_b128 v[148:151], v140 offset:9248
	ds_read_b128 v[152:155], v140 offset:9280
	ds_read_b128 v[156:159], v140 offset:9312
	ds_read_b128 v[160:163], v140 offset:13824
	ds_read_b128 v[164:167], v140 offset:13856
	s_waitcnt lgkmcnt(5)
	v_mfma_f32_32x32x16_bf16 v[64:79], v[144:147], v[184:187], 0
	ds_read_b128 v[168:171], v140 offset:13888
	v_exp_f32_e32 v32, v32
	v_exp_f32_e32 v33, v33
	v_add_f32_e32 v130, v130, v32
	v_add_f32_e32 v131, v131, v33
	v_cvt_pk_bf16_f32 v96, v32, v33
	v_exp_f32_e32 v34, v34
	v_exp_f32_e32 v35, v35
	v_add_f32_e32 v130, v130, v34
	v_add_f32_e32 v131, v131, v35
	v_cvt_pk_bf16_f32 v97, v34, v35
	s_waitcnt vmcnt(3)
	v_add_u32_e32 v128, s68, v179
	ds_write_b128 v128, v[208:211]
	global_load_dwordx4 v[208:211], v232, s[16:17]
	s_waitcnt lgkmcnt(6)
	v_mfma_f32_32x32x16_bf16 v[64:79], v[148:151], v[188:191], v[64:79]
	ds_read_b128 v[172:175], v140 offset:13920
	v_exp_f32_e32 v36, v36
	v_exp_f32_e32 v37, v37
	v_add_f32_e32 v130, v130, v36
	v_add_f32_e32 v131, v131, v37
	v_cvt_pk_bf16_f32 v98, v36, v37
	v_exp_f32_e32 v38, v38
	v_exp_f32_e32 v39, v39
	v_add_f32_e32 v130, v130, v38
	v_add_f32_e32 v131, v131, v39
	v_cvt_pk_bf16_f32 v99, v38, v39
	s_waitcnt vmcnt(3)
	v_add_u32_e32 v128, s68, v181
	ds_write_b128 v128, v[212:215]
	global_load_dwordx4 v[212:215], v239, s[16:17]
	s_waitcnt lgkmcnt(7)
	v_mfma_f32_32x32x16_bf16 v[64:79], v[152:155], v[192:195], v[64:79]
	ds_read_b128 v[144:147], v141 offset:0
	v_exp_f32_e32 v40, v40
	v_exp_f32_e32 v41, v41
	v_add_f32_e32 v130, v130, v40
	v_add_f32_e32 v131, v131, v41
	v_cvt_pk_bf16_f32 v100, v40, v41
	v_exp_f32_e32 v42, v42
	v_exp_f32_e32 v43, v43
	v_add_f32_e32 v130, v130, v42
	v_add_f32_e32 v131, v131, v43
	v_cvt_pk_bf16_f32 v101, v42, v43
	s_waitcnt vmcnt(3)
	v_add_u32_e32 v128, s71, v183
	ds_write_b128 v128, v[220:223]
	global_load_dwordx4 v[220:223], v232, s[22:23]
	s_waitcnt lgkmcnt(8)
	v_mfma_f32_32x32x16_bf16 v[64:79], v[156:159], v[196:199], v[64:79]
	ds_read_b128 v[148:151], v141 offset:32
	v_exp_f32_e32 v44, v44
	v_exp_f32_e32 v45, v45
	v_add_f32_e32 v130, v130, v44
	v_add_f32_e32 v131, v131, v45
	v_cvt_pk_bf16_f32 v102, v44, v45
	v_exp_f32_e32 v46, v46
	v_exp_f32_e32 v47, v47
	v_add_f32_e32 v130, v130, v46
	v_add_f32_e32 v131, v131, v47
	v_cvt_pk_bf16_f32 v103, v46, v47
	s_waitcnt vmcnt(3)
	v_add_u32_e32 v128, s71, v183
	ds_write_b128 v128, v[224:227] offset:8192
	global_load_dwordx4 v[224:227], v239, s[22:23]
	s_waitcnt lgkmcnt(9)
	v_mfma_f32_32x32x16_bf16 v[80:95], v[160:163], v[184:187], 0
	ds_read_b128 v[152:155], v141 offset:64
	v_exp_f32_e32 v48, v48
	v_exp_f32_e32 v49, v49
	v_add_f32_e32 v130, v130, v48
	v_add_f32_e32 v131, v131, v49
	v_cvt_pk_bf16_f32 v104, v48, v49
	v_exp_f32_e32 v50, v50
	v_exp_f32_e32 v51, v51
	v_add_f32_e32 v130, v130, v50
	v_add_f32_e32 v131, v131, v51
	v_cvt_pk_bf16_f32 v105, v50, v51
	s_waitcnt lgkmcnt(9)
	v_mfma_f32_32x32x16_bf16 v[80:95], v[164:167], v[188:191], v[80:95]
	ds_read_b128 v[156:159], v141 offset:96
	v_exp_f32_e32 v52, v52
	v_exp_f32_e32 v53, v53
	v_add_f32_e32 v130, v130, v52
	v_add_f32_e32 v131, v131, v53
	v_cvt_pk_bf16_f32 v106, v52, v53
	v_exp_f32_e32 v54, v54
	v_exp_f32_e32 v55, v55
	v_add_f32_e32 v130, v130, v54
	v_add_f32_e32 v131, v131, v55
	v_cvt_pk_bf16_f32 v107, v54, v55
	s_waitcnt lgkmcnt(9)
	v_mfma_f32_32x32x16_bf16 v[80:95], v[168:171], v[192:195], v[80:95]
	ds_read_b128 v[160:163], v141 offset:4608
	v_exp_f32_e32 v56, v56
	v_exp_f32_e32 v57, v57
	v_add_f32_e32 v130, v130, v56
	v_add_f32_e32 v131, v131, v57
	v_cvt_pk_bf16_f32 v108, v56, v57
	v_exp_f32_e32 v58, v58
	v_exp_f32_e32 v59, v59
	v_add_f32_e32 v130, v130, v58
	v_add_f32_e32 v131, v131, v59
	v_cvt_pk_bf16_f32 v109, v58, v59
	s_waitcnt lgkmcnt(8)
	v_mfma_f32_32x32x16_bf16 v[80:95], v[172:175], v[196:199], v[80:95]
	ds_read_b128 v[164:167], v141 offset:4640
	v_exp_f32_e32 v60, v60
	v_exp_f32_e32 v61, v61
	v_add_f32_e32 v130, v130, v60
	v_add_f32_e32 v131, v131, v61
	v_cvt_pk_bf16_f32 v110, v60, v61
	v_exp_f32_e32 v62, v62
	v_exp_f32_e32 v63, v63
	v_add_f32_e32 v130, v130, v62
	v_add_f32_e32 v131, v131, v63
	v_cvt_pk_bf16_f32 v111, v62, v63
	s_add_u32 s16, s16, 16384
	s_addc_u32 s17, s17, 0
	s_add_u32 s22, s22, 16384
	s_addc_u32 s23, s23, 0
	s_waitcnt lgkmcnt(7)
	v_mfma_f32_32x32x16_bf16 v[32:47], v[144:147], v[184:187], 0
	ds_read_b128 v[168:171], v141 offset:4672
	v_exp_f32_e32 v64, v64
	v_exp_f32_e32 v65, v65
	v_add_f32_e32 v130, v130, v64
	v_add_f32_e32 v131, v131, v65
	v_cvt_pk_bf16_f32 v112, v64, v65
	s_waitcnt lgkmcnt(6)
	v_mfma_f32_32x32x16_bf16 v[32:47], v[148:151], v[188:191], v[32:47]
	ds_read_b128 v[172:175], v141 offset:4704
	v_exp_f32_e32 v66, v66
	v_exp_f32_e32 v67, v67
	v_add_f32_e32 v130, v130, v66
	v_add_f32_e32 v131, v131, v67
	v_cvt_pk_bf16_f32 v113, v66, v67
	s_waitcnt lgkmcnt(5)
	v_mfma_f32_32x32x16_bf16 v[32:47], v[152:155], v[192:195], v[32:47]
	ds_read_b64_tr_b16 v[144:145], v177 offset:0
	ds_read_b64_tr_b16 v[146:147], v177 offset:1024
	v_exp_f32_e32 v68, v68
	v_exp_f32_e32 v69, v69
	v_add_f32_e32 v130, v130, v68
	v_add_f32_e32 v131, v131, v69
	v_cvt_pk_bf16_f32 v114, v68, v69
	s_waitcnt lgkmcnt(6)
	v_mfma_f32_32x32x16_bf16 v[32:47], v[156:159], v[196:199], v[32:47]
	ds_read_b64_tr_b16 v[148:149], v177 offset:512
	ds_read_b64_tr_b16 v[150:151], v177 offset:1536
	v_exp_f32_e32 v70, v70
	v_exp_f32_e32 v71, v71
	v_add_f32_e32 v130, v130, v70
	v_add_f32_e32 v131, v131, v71
	v_cvt_pk_bf16_f32 v115, v70, v71
	s_waitcnt lgkmcnt(7)
	v_mfma_f32_32x32x16_bf16 v[48:63], v[160:163], v[184:187], 0
	ds_read_b64_tr_b16 v[152:153], v177 offset:2048
	ds_read_b64_tr_b16 v[154:155], v177 offset:3072
	v_exp_f32_e32 v72, v72
	v_exp_f32_e32 v73, v73
	v_add_f32_e32 v130, v130, v72
	v_add_f32_e32 v131, v131, v73
	v_cvt_pk_bf16_f32 v116, v72, v73
	s_waitcnt lgkmcnt(8)
	v_mfma_f32_32x32x16_bf16 v[48:63], v[164:167], v[188:191], v[48:63]
	ds_read_b64_tr_b16 v[156:157], v177 offset:2560
	ds_read_b64_tr_b16 v[158:159], v177 offset:3584
	v_exp_f32_e32 v74, v74
	v_exp_f32_e32 v75, v75
	v_add_f32_e32 v130, v130, v74
	v_add_f32_e32 v131, v131, v75
	v_cvt_pk_bf16_f32 v117, v74, v75
	s_waitcnt lgkmcnt(9)
	v_mfma_f32_32x32x16_bf16 v[48:63], v[168:171], v[192:195], v[48:63]
	ds_read_b64_tr_b16 v[160:161], v177 offset:4096
	ds_read_b64_tr_b16 v[162:163], v177 offset:5120
	v_exp_f32_e32 v76, v76
	v_exp_f32_e32 v77, v77
	v_add_f32_e32 v130, v130, v76
	v_add_f32_e32 v131, v131, v77
	v_cvt_pk_bf16_f32 v118, v76, v77
	s_waitcnt lgkmcnt(10)
	v_mfma_f32_32x32x16_bf16 v[48:63], v[172:175], v[196:199], v[48:63]
	ds_read_b64_tr_b16 v[164:165], v177 offset:4608
	ds_read_b64_tr_b16 v[166:167], v177 offset:5632
	v_exp_f32_e32 v78, v78
	v_exp_f32_e32 v79, v79
	v_add_f32_e32 v130, v130, v78
	v_add_f32_e32 v131, v131, v79
	v_cvt_pk_bf16_f32 v119, v78, v79
	s_waitcnt lgkmcnt(10)
	v_mfma_f32_32x32x16_bf16 v[0:15], v[144:147], v[96:99], v[0:15]
	ds_read_b64_tr_b16 v[168:169], v177 offset:6144
	ds_read_b64_tr_b16 v[170:171], v177 offset:7168
	v_exp_f32_e32 v80, v80
	v_exp_f32_e32 v81, v81
	v_add_f32_e32 v130, v130, v80
	v_add_f32_e32 v131, v131, v81
	v_cvt_pk_bf16_f32 v120, v80, v81
	s_waitcnt lgkmcnt(10)
	v_mfma_f32_32x32x16_bf16 v[16:31], v[148:151], v[96:99], v[16:31]
	ds_read_b64_tr_b16 v[172:173], v177 offset:6656
	ds_read_b64_tr_b16 v[174:175], v177 offset:7680
	v_exp_f32_e32 v82, v82
	v_exp_f32_e32 v83, v83
	v_add_f32_e32 v130, v130, v82
	v_add_f32_e32 v131, v131, v83
	v_cvt_pk_bf16_f32 v121, v82, v83
	s_waitcnt lgkmcnt(10)
	v_mfma_f32_32x32x16_bf16 v[0:15], v[152:155], v[100:103], v[0:15]
	ds_read_b128 v[144:147], v141 offset:9216
	v_exp_f32_e32 v84, v84
	v_exp_f32_e32 v85, v85
	v_add_f32_e32 v130, v130, v84
	v_add_f32_e32 v131, v131, v85
	v_cvt_pk_bf16_f32 v122, v84, v85
	s_waitcnt lgkmcnt(9)
	v_mfma_f32_32x32x16_bf16 v[16:31], v[156:159], v[100:103], v[16:31]
	ds_read_b128 v[148:151], v141 offset:9248
	v_exp_f32_e32 v86, v86
	v_exp_f32_e32 v87, v87
	v_add_f32_e32 v130, v130, v86
	v_add_f32_e32 v131, v131, v87
	v_cvt_pk_bf16_f32 v123, v86, v87
	s_waitcnt lgkmcnt(8)
	v_mfma_f32_32x32x16_bf16 v[0:15], v[160:163], v[104:107], v[0:15]
	ds_read_b128 v[152:155], v141 offset:9280
	v_exp_f32_e32 v88, v88
	v_exp_f32_e32 v89, v89
	v_add_f32_e32 v130, v130, v88
	v_add_f32_e32 v131, v131, v89
	v_cvt_pk_bf16_f32 v124, v88, v89
	s_waitcnt lgkmcnt(7)
	v_mfma_f32_32x32x16_bf16 v[16:31], v[164:167], v[104:107], v[16:31]
	ds_read_b128 v[156:159], v141 offset:9312
	v_exp_f32_e32 v90, v90
	v_exp_f32_e32 v91, v91
	v_add_f32_e32 v130, v130, v90
	v_add_f32_e32 v131, v131, v91
	v_cvt_pk_bf16_f32 v125, v90, v91
	s_waitcnt lgkmcnt(6)
	v_mfma_f32_32x32x16_bf16 v[0:15], v[168:171], v[108:111], v[0:15]
	ds_read_b128 v[160:163], v141 offset:13824
	v_exp_f32_e32 v92, v92
	v_exp_f32_e32 v93, v93
	v_add_f32_e32 v130, v130, v92
	v_add_f32_e32 v131, v131, v93
	v_cvt_pk_bf16_f32 v126, v92, v93
	s_waitcnt lgkmcnt(5)
	v_mfma_f32_32x32x16_bf16 v[16:31], v[172:175], v[108:111], v[16:31]
	ds_read_b128 v[164:167], v141 offset:13856
	v_exp_f32_e32 v94, v94
	v_exp_f32_e32 v95, v95
	v_add_f32_e32 v130, v130, v94
	v_add_f32_e32 v131, v131, v95
	v_cvt_pk_bf16_f32 v127, v94, v95
	s_mov_b32 s0, s64
	s_mov_b32 s64, s65
	s_mov_b32 s65, s68
	s_mov_b32 s68, s0
	s_mov_b32 s0, s69
	s_mov_b32 s69, s70
	s_mov_b32 s70, s71
	s_mov_b32 s71, s0
	s_barrier
	s_cmp_eq_u32 s27, 0
	s_cbranch_scc1 .Lat_g_last
.Lat_g_loop:
	v_add_u32_e32 v140, s64, v237
	v_add_u32_e32 v141, s65, v237
	v_add_u32_e32 v176, s69, v238
	v_add_u32_e32 v177, s70, v238
	s_waitcnt lgkmcnt(5)
	v_mfma_f32_32x32x16_bf16 v[64:79], v[144:147], v[184:187], 0
	ds_read_b128 v[168:171], v140 offset:13888
	v_exp_f32_e32 v32, v32
	v_exp_f32_e32 v33, v33
	v_add_f32_e32 v130, v130, v32
	v_add_f32_e32 v131, v131, v33
	v_cvt_pk_bf16_f32 v96, v32, v33
	s_waitcnt vmcnt(3)
	v_add_u32_e32 v128, s68, v179
	ds_write_b128 v128, v[208:211]
	global_load_dwordx4 v[208:211], v232, s[16:17]
	s_waitcnt lgkmcnt(6)
	v_mfma_f32_32x32x16_bf16 v[64:79], v[148:151], v[188:191], v[64:79]
	ds_read_b128 v[172:175], v140 offset:13920
	v_exp_f32_e32 v34, v34
	v_exp_f32_e32 v35, v35
	v_add_f32_e32 v130, v130, v34
	v_add_f32_e32 v131, v131, v35
	v_cvt_pk_bf16_f32 v97, v34, v35
	s_waitcnt vmcnt(3)
	v_add_u32_e32 v128, s68, v181
	ds_write_b128 v128, v[212:215]
	global_load_dwordx4 v[212:215], v239, s[16:17]
	s_waitcnt lgkmcnt(7)
	v_mfma_f32_32x32x16_bf16 v[64:79], v[152:155], v[192:195], v[64:79]
	ds_read_b64_tr_b16 v[144:145], v176 offset:8192
	ds_read_b64_tr_b16 v[146:147], v176 offset:9216
	v_exp_f32_e32 v36, v36
	v_exp_f32_e32 v37, v37
	v_add_f32_e32 v130, v130, v36
	v_add_f32_e32 v131, v131, v37
	v_cvt_pk_bf16_f32 v98, v36, v37
	s_waitcnt vmcnt(3)
	v_add_u32_e32 v128, s71, v183
	ds_write_b128 v128, v[220:223]
	global_load_dwordx4 v[220:223], v232, s[22:23]
	s_waitcnt lgkmcnt(9)
	v_mfma_f32_32x32x16_bf16 v[64:79], v[156:159], v[196:199], v[64:79]
	ds_read_b64_tr_b16 v[148:149], v176 offset:8704
	ds_read_b64_tr_b16 v[150:151], v176 offset:9728
	v_exp_f32_e32 v38, v38
	v_exp_f32_e32 v39, v39
	v_add_f32_e32 v130, v130, v38
	v_add_f32_e32 v131, v131, v39
	v_cvt_pk_bf16_f32 v99, v38, v39
	s_waitcnt vmcnt(3)
	v_add_u32_e32 v128, s71, v183
	ds_write_b128 v128, v[224:227] offset:8192
	global_load_dwordx4 v[224:227], v239, s[22:23]
	s_waitcnt lgkmcnt(11)
	v_mfma_f32_32x32x16_bf16 v[80:95], v[160:163], v[184:187], 0
	ds_read_b64_tr_b16 v[152:153], v176 offset:10240
	ds_read_b64_tr_b16 v[154:155], v176 offset:11264
	v_exp_f32_e32 v40, v40
	v_exp_f32_e32 v41, v41
	v_add_f32_e32 v130, v130, v40
	v_add_f32_e32 v131, v131, v41
	v_cvt_pk_bf16_f32 v100, v40, v41
	s_waitcnt lgkmcnt(12)
	v_mfma_f32_32x32x16_bf16 v[80:95], v[164:167], v[188:191], v[80:95]
	ds_read_b64_tr_b16 v[156:157], v176 offset:10752
	ds_read_b64_tr_b16 v[158:159], v176 offset:11776
	v_exp_f32_e32 v42, v42
	v_exp_f32_e32 v43, v43
	v_add_f32_e32 v130, v130, v42
	v_add_f32_e32 v131, v131, v43
	v_cvt_pk_bf16_f32 v101, v42, v43
	s_waitcnt lgkmcnt(13)
	v_mfma_f32_32x32x16_bf16 v[80:95], v[168:171], v[192:195], v[80:95]
	ds_read_b64_tr_b16 v[160:161], v176 offset:12288
	ds_read_b64_tr_b16 v[162:163], v176 offset:13312
	v_exp_f32_e32 v44, v44
	v_exp_f32_e32 v45, v45
	v_add_f32_e32 v130, v130, v44
	v_add_f32_e32 v131, v131, v45
	v_cvt_pk_bf16_f32 v102, v44, v45
	s_waitcnt lgkmcnt(13)
	v_mfma_f32_32x32x16_bf16 v[80:95], v[172:175], v[196:199], v[80:95]
	ds_read_b64_tr_b16 v[164:165], v176 offset:12800
	ds_read_b64_tr_b16 v[166:167], v176 offset:13824
	v_exp_f32_e32 v46, v46
	v_exp_f32_e32 v47, v47
	v_add_f32_e32 v130, v130, v46
	v_add_f32_e32 v131, v131, v47
	v_cvt_pk_bf16_f32 v103, v46, v47
	s_waitcnt lgkmcnt(12)
	v_mfma_f32_32x32x16_bf16 v[0:15], v[144:147], v[112:115], v[0:15]
	ds_read_b64_tr_b16 v[168:169], v176 offset:14336
	ds_read_b64_tr_b16 v[170:171], v176 offset:15360
	v_exp_f32_e32 v48, v48
	v_exp_f32_e32 v49, v49
	v_add_f32_e32 v130, v130, v48
	v_add_f32_e32 v131, v131, v49
	v_cvt_pk_bf16_f32 v104, v48, v49
	s_waitcnt lgkmcnt(11)
	v_mfma_f32_32x32x16_bf16 v[16:31], v[148:151], v[112:115], v[16:31]
	ds_read_b64_tr_b16 v[172:173], v176 offset:14848
	ds_read_b64_tr_b16 v[174:175], v176 offset:15872
	v_exp_f32_e32 v50, v50
	v_exp_f32_e32 v51, v51
	v_add_f32_e32 v130, v130, v50
	v_add_f32_e32 v131, v131, v51
	v_cvt_pk_bf16_f32 v105, v50, v51
	s_waitcnt lgkmcnt(10)
	v_mfma_f32_32x32x16_bf16 v[0:15], v[152:155], v[116:119], v[0:15]
	ds_read_b128 v[144:147], v141 offset:0
	v_exp_f32_e32 v52, v52
	v_exp_f32_e32 v53, v53
	v_add_f32_e32 v130, v130, v52
	v_add_f32_e32 v131, v131, v53
	v_cvt_pk_bf16_f32 v106, v52, v53
	s_waitcnt lgkmcnt(9)
	v_mfma_f32_32x32x16_bf16 v[16:31], v[156:159], v[116:119], v[16:31]
	ds_read_b128 v[148:151], v141 offset:32
	v_exp_f32_e32 v54, v54
	v_exp_f32_e32 v55, v55
	v_add_f32_e32 v130, v130, v54
	v_add_f32_e32 v131, v131, v55
	v_cvt_pk_bf16_f32 v107, v54, v55
	s_waitcnt lgkmcnt(8)
	v_mfma_f32_32x32x16_bf16 v[0:15], v[160:163], v[120:123], v[0:15]
	ds_read_b128 v[152:155], v141 offset:64
	v_exp_f32_e32 v56, v56
	v_exp_f32_e32 v57, v57
	v_add_f32_e32 v130, v130, v56
	v_add_f32_e32 v131, v131, v57
	v_cvt_pk_bf16_f32 v108, v56, v57
	s_waitcnt lgkmcnt(7)
	v_mfma_f32_32x32x16_bf16 v[16:31], v[164:167], v[120:123], v[16:31]
	ds_read_b128 v[156:159], v141 offset:96
	v_exp_f32_e32 v58, v58
	v_exp_f32_e32 v59, v59
	v_add_f32_e32 v130, v130, v58
	v_add_f32_e32 v131, v131, v59
	v_cvt_pk_bf16_f32 v109, v58, v59
	s_waitcnt lgkmcnt(6)
	v_mfma_f32_32x32x16_bf16 v[0:15], v[168:171], v[124:127], v[0:15]
	ds_read_b128 v[160:163], v141 offset:4608
	v_exp_f32_e32 v60, v60
	v_exp_f32_e32 v61, v61
	v_add_f32_e32 v130, v130, v60
	v_add_f32_e32 v131, v131, v61
	v_cvt_pk_bf16_f32 v110, v60, v61
	s_waitcnt lgkmcnt(5)
	v_mfma_f32_32x32x16_bf16 v[16:31], v[172:175], v[124:127], v[16:31]
	ds_read_b128 v[164:167], v141 offset:4640
	v_exp_f32_e32 v62, v62
	v_exp_f32_e32 v63, v63
	v_add_f32_e32 v130, v130, v62
	v_add_f32_e32 v131, v131, v63
	v_cvt_pk_bf16_f32 v111, v62, v63
	s_add_u32 s16, s16, 16384
	s_addc_u32 s17, s17, 0
	s_add_u32 s22, s22, 16384
	s_addc_u32 s23, s23, 0
	s_waitcnt lgkmcnt(5)
	v_mfma_f32_32x32x16_bf16 v[32:47], v[144:147], v[184:187], 0
	ds_read_b128 v[168:171], v141 offset:4672
	v_exp_f32_e32 v64, v64
	v_exp_f32_e32 v65, v65
	v_add_f32_e32 v130, v130, v64
	v_add_f32_e32 v131, v131, v65
	v_cvt_pk_bf16_f32 v112, v64, v65
	s_waitcnt lgkmcnt(5)
	v_mfma_f32_32x32x16_bf16 v[32:47], v[148:151], v[188:191], v[32:47]
	ds_read_b128 v[172:175], v141 offset:4704
	v_exp_f32_e32 v66, v66
	v_exp_f32_e32 v67, v67
	v_add_f32_e32 v130, v130, v66
	v_add_f32_e32 v131, v131, v67
	v_cvt_pk_bf16_f32 v113, v66, v67
	s_waitcnt lgkmcnt(5)
	v_mfma_f32_32x32x16_bf16 v[32:47], v[152:155], v[192:195], v[32:47]
	ds_read_b64_tr_b16 v[144:145], v177 offset:0
	ds_read_b64_tr_b16 v[146:147], v177 offset:1024
	v_exp_f32_e32 v68, v68
	v_exp_f32_e32 v69, v69
	v_add_f32_e32 v130, v130, v68
	v_add_f32_e32 v131, v131, v69
	v_cvt_pk_bf16_f32 v114, v68, v69
	s_waitcnt lgkmcnt(6)
	v_mfma_f32_32x32x16_bf16 v[32:47], v[156:159], v[196:199], v[32:47]
	ds_read_b64_tr_b16 v[148:149], v177 offset:512
	ds_read_b64_tr_b16 v[150:151], v177 offset:1536
	v_exp_f32_e32 v70, v70
	v_exp_f32_e32 v71, v71
	v_add_f32_e32 v130, v130, v70
	v_add_f32_e32 v131, v131, v71
	v_cvt_pk_bf16_f32 v115, v70, v71
	s_waitcnt lgkmcnt(7)
	v_mfma_f32_32x32x16_bf16 v[48:63], v[160:163], v[184:187], 0
	ds_read_b64_tr_b16 v[152:153], v177 offset:2048
	ds_read_b64_tr_b16 v[154:155], v177 offset:3072
	v_exp_f32_e32 v72, v72
	v_exp_f32_e32 v73, v73
	v_add_f32_e32 v130, v130, v72
	v_add_f32_e32 v131, v131, v73
	v_cvt_pk_bf16_f32 v116, v72, v73
	s_waitcnt lgkmcnt(8)
	v_mfma_f32_32x32x16_bf16 v[48:63], v[164:167], v[188:191], v[48:63]
	ds_read_b64_tr_b16 v[156:157], v177 offset:2560
	ds_read_b64_tr_b16 v[158:159], v177 offset:3584
	v_exp_f32_e32 v74, v74
	v_exp_f32_e32 v75, v75
	v_add_f32_e32 v130, v130, v74
	v_add_f32_e32 v131, v131, v75
	v_cvt_pk_bf16_f32 v117, v74, v75
	s_waitcnt lgkmcnt(9)
	v_mfma_f32_32x32x16_bf16 v[48:63], v[168:171], v[192:195], v[48:63]
	ds_read_b64_tr_b16 v[160:161], v177 offset:4096
	ds_read_b64_tr_b16 v[162:163], v177 offset:5120
	v_exp_f32_e32 v76, v76
	v_exp_f32_e32 v77, v77
	v_add_f32_e32 v130, v130, v76
	v_add_f32_e32 v131, v131, v77
	v_cvt_pk_bf16_f32 v118, v76, v77
	s_waitcnt lgkmcnt(10)
	v_mfma_f32_32x32x16_bf16 v[48:63], v[172:175], v[196:199], v[48:63]
	ds_read_b64_tr_b16 v[164:165], v177 offset:4608
	ds_read_b64_tr_b16 v[166:167], v177 offset:5632
	v_exp_f32_e32 v78, v78
	v_exp_f32_e32 v79, v79
	v_add_f32_e32 v130, v130, v78
	v_add_f32_e32 v131, v131, v79
	v_cvt_pk_bf16_f32 v119, v78, v79
	s_waitcnt lgkmcnt(10)
	v_mfma_f32_32x32x16_bf16 v[0:15], v[144:147], v[96:99], v[0:15]
	ds_read_b64_tr_b16 v[168:169], v177 offset:6144
	ds_read_b64_tr_b16 v[170:171], v177 offset:7168
	v_exp_f32_e32 v80, v80
	v_exp_f32_e32 v81, v81
	v_add_f32_e32 v130, v130, v80
	v_add_f32_e32 v131, v131, v81
	v_cvt_pk_bf16_f32 v120, v80, v81
	s_waitcnt lgkmcnt(10)
	v_mfma_f32_32x32x16_bf16 v[16:31], v[148:151], v[96:99], v[16:31]
	ds_read_b64_tr_b16 v[172:173], v177 offset:6656
	ds_read_b64_tr_b16 v[174:175], v177 offset:7680
	v_exp_f32_e32 v82, v82
	v_exp_f32_e32 v83, v83
	v_add_f32_e32 v130, v130, v82
	v_add_f32_e32 v131, v131, v83
	v_cvt_pk_bf16_f32 v121, v82, v83
	s_waitcnt lgkmcnt(10)
	v_mfma_f32_32x32x16_bf16 v[0:15], v[152:155], v[100:103], v[0:15]
	ds_read_b128 v[144:147], v141 offset:9216
	v_exp_f32_e32 v84, v84
	v_exp_f32_e32 v85, v85
	v_add_f32_e32 v130, v130, v84
	v_add_f32_e32 v131, v131, v85
	v_cvt_pk_bf16_f32 v122, v84, v85
	s_waitcnt lgkmcnt(9)
	v_mfma_f32_32x32x16_bf16 v[16:31], v[156:159], v[100:103], v[16:31]
	ds_read_b128 v[148:151], v141 offset:9248
	v_exp_f32_e32 v86, v86
	v_exp_f32_e32 v87, v87
	v_add_f32_e32 v130, v130, v86
	v_add_f32_e32 v131, v131, v87
	v_cvt_pk_bf16_f32 v123, v86, v87
	s_waitcnt lgkmcnt(8)
	v_mfma_f32_32x32x16_bf16 v[0:15], v[160:163], v[104:107], v[0:15]
	ds_read_b128 v[152:155], v141 offset:9280
	v_exp_f32_e32 v88, v88
	v_exp_f32_e32 v89, v89
	v_add_f32_e32 v130, v130, v88
	v_add_f32_e32 v131, v131, v89
	v_cvt_pk_bf16_f32 v124, v88, v89
	s_waitcnt lgkmcnt(7)
	v_mfma_f32_32x32x16_bf16 v[16:31], v[164:167], v[104:107], v[16:31]
	ds_read_b128 v[156:159], v141 offset:9312
	v_exp_f32_e32 v90, v90
	v_exp_f32_e32 v91, v91
	v_add_f32_e32 v130, v130, v90
	v_add_f32_e32 v131, v131, v91
	v_cvt_pk_bf16_f32 v125, v90, v91
	s_waitcnt lgkmcnt(6)
	v_mfma_f32_32x32x16_bf16 v[0:15], v[168:171], v[108:111], v[0:15]
	ds_read_b128 v[160:163], v141 offset:13824
	v_exp_f32_e32 v92, v92
	v_exp_f32_e32 v93, v93
	v_add_f32_e32 v130, v130, v92
	v_add_f32_e32 v131, v131, v93
	v_cvt_pk_bf16_f32 v126, v92, v93
	s_waitcnt lgkmcnt(5)
	v_mfma_f32_32x32x16_bf16 v[16:31], v[172:175], v[108:111], v[16:31]
	ds_read_b128 v[164:167], v141 offset:13856
	v_exp_f32_e32 v94, v94
	v_exp_f32_e32 v95, v95
	v_add_f32_e32 v130, v130, v94
	v_add_f32_e32 v131, v131, v95
	v_cvt_pk_bf16_f32 v127, v94, v95
	s_mov_b32 s0, s64
	s_mov_b32 s64, s65
	s_mov_b32 s65, s68
	s_mov_b32 s68, s0
	s_mov_b32 s0, s69
	s_mov_b32 s69, s70
	s_mov_b32 s70, s71
	s_mov_b32 s71, s0
	s_add_i32 s27, s27, -1
	s_barrier
	s_cmp_lg_u32 s27, 0
	s_cbranch_scc1 .Lat_g_loop
.Lat_g_last:
	v_add_u32_e32 v140, s64, v237
	v_add_u32_e32 v141, s65, v237
	v_add_u32_e32 v176, s69, v238
	v_add_u32_e32 v177, s70, v238
	s_waitcnt lgkmcnt(5)
	v_mfma_f32_32x32x16_bf16 v[64:79], v[144:147], v[184:187], 0
	ds_read_b128 v[168:171], v140 offset:13888
	v_exp_f32_e32 v32, v32
	v_exp_f32_e32 v33, v33
	v_add_f32_e32 v130, v130, v32
	v_add_f32_e32 v131, v131, v33
	v_cvt_pk_bf16_f32 v96, v32, v33
	s_waitcnt lgkmcnt(5)
	v_mfma_f32_32x32x16_bf16 v[64:79], v[148:151], v[188:191], v[64:79]
	ds_read_b128 v[172:175], v140 offset:13920
	v_exp_f32_e32 v34, v34
	v_exp_f32_e32 v35, v35
	v_add_f32_e32 v130, v130, v34
	v_add_f32_e32 v131, v131, v35
	v_cvt_pk_bf16_f32 v97, v34, v35
	s_waitcnt lgkmcnt(5)
	v_mfma_f32_32x32x16_bf16 v[64:79], v[152:155], v[192:195], v[64:79]
	ds_read_b64_tr_b16 v[144:145], v176 offset:8192
	ds_read_b64_tr_b16 v[146:147], v176 offset:9216
	v_exp_f32_e32 v36, v36
	v_exp_f32_e32 v37, v37
	v_add_f32_e32 v130, v130, v36
	v_add_f32_e32 v131, v131, v37
	v_cvt_pk_bf16_f32 v98, v36, v37
	s_waitcnt lgkmcnt(6)
	v_mfma_f32_32x32x16_bf16 v[64:79], v[156:159], v[196:199], v[64:79]
	ds_read_b64_tr_b16 v[148:149], v176 offset:8704
	ds_read_b64_tr_b16 v[150:151], v176 offset:9728
	v_exp_f32_e32 v38, v38
	v_exp_f32_e32 v39, v39
	v_add_f32_e32 v130, v130, v38
	v_add_f32_e32 v131, v131, v39
	v_cvt_pk_bf16_f32 v99, v38, v39
	s_waitcnt lgkmcnt(7)
	v_mfma_f32_32x32x16_bf16 v[80:95], v[160:163], v[184:187], 0
	ds_read_b64_tr_b16 v[152:153], v176 offset:10240
	ds_read_b64_tr_b16 v[154:155], v176 offset:11264
	v_exp_f32_e32 v40, v40
	v_exp_f32_e32 v41, v41
	v_add_f32_e32 v130, v130, v40
	v_add_f32_e32 v131, v131, v41
	v_cvt_pk_bf16_f32 v100, v40, v41
	s_waitcnt lgkmcnt(8)
	v_mfma_f32_32x32x16_bf16 v[80:95], v[164:167], v[188:191], v[80:95]
	ds_read_b64_tr_b16 v[156:157], v176 offset:10752
	ds_read_b64_tr_b16 v[158:159], v176 offset:11776
	v_exp_f32_e32 v42, v42
	v_exp_f32_e32 v43, v43
	v_add_f32_e32 v130, v130, v42
	v_add_f32_e32 v131, v131, v43
	v_cvt_pk_bf16_f32 v101, v42, v43
	s_waitcnt lgkmcnt(9)
	v_mfma_f32_32x32x16_bf16 v[80:95], v[168:171], v[192:195], v[80:95]
	ds_read_b64_tr_b16 v[160:161], v176 offset:12288
	ds_read_b64_tr_b16 v[162:163], v176 offset:13312
	v_exp_f32_e32 v44, v44
	v_exp_f32_e32 v45, v45
	v_add_f32_e32 v130, v130, v44
	v_add_f32_e32 v131, v131, v45
	v_cvt_pk_bf16_f32 v102, v44, v45
	s_waitcnt lgkmcnt(10)
	v_mfma_f32_32x32x16_bf16 v[80:95], v[172:175], v[196:199], v[80:95]
	ds_read_b64_tr_b16 v[164:165], v176 offset:12800
	ds_read_b64_tr_b16 v[166:167], v176 offset:13824
	v_exp_f32_e32 v46, v46
	v_exp_f32_e32 v47, v47
	v_add_f32_e32 v130, v130, v46
	v_add_f32_e32 v131, v131, v47
	v_cvt_pk_bf16_f32 v103, v46, v47
	s_waitcnt lgkmcnt(10)
	v_mfma_f32_32x32x16_bf16 v[0:15], v[144:147], v[112:115], v[0:15]
	ds_read_b64_tr_b16 v[168:169], v176 offset:14336
	ds_read_b64_tr_b16 v[170:171], v176 offset:15360
	v_exp_f32_e32 v48, v48
	v_exp_f32_e32 v49, v49
	v_add_f32_e32 v130, v130, v48
	v_add_f32_e32 v131, v131, v49
	v_cvt_pk_bf16_f32 v104, v48, v49
	s_waitcnt lgkmcnt(10)
	v_mfma_f32_32x32x16_bf16 v[16:31], v[148:151], v[112:115], v[16:31]
	ds_read_b64_tr_b16 v[172:173], v176 offset:14848
	ds_read_b64_tr_b16 v[174:175], v176 offset:15872
	v_exp_f32_e32 v50, v50
	v_exp_f32_e32 v51, v51
	v_add_f32_e32 v130, v130, v50
	v_add_f32_e32 v131, v131, v51
	v_cvt_pk_bf16_f32 v105, v50, v51
	s_waitcnt lgkmcnt(10)
	v_mfma_f32_32x32x16_bf16 v[0:15], v[152:155], v[116:119], v[0:15]
	ds_read_b64_tr_b16 v[144:145], v177 offset:0
	ds_read_b64_tr_b16 v[146:147], v177 offset:1024
	v_exp_f32_e32 v52, v52
	v_exp_f32_e32 v53, v53
	v_add_f32_e32 v130, v130, v52
	v_add_f32_e32 v131, v131, v53
	v_cvt_pk_bf16_f32 v106, v52, v53
	s_waitcnt lgkmcnt(10)
	v_mfma_f32_32x32x16_bf16 v[16:31], v[156:159], v[116:119], v[16:31]
	ds_read_b64_tr_b16 v[148:149], v177 offset:512
	ds_read_b64_tr_b16 v[150:151], v177 offset:1536
	v_exp_f32_e32 v54, v54
	v_exp_f32_e32 v55, v55
	v_add_f32_e32 v130, v130, v54
	v_add_f32_e32 v131, v131, v55
	v_cvt_pk_bf16_f32 v107, v54, v55
	s_waitcnt lgkmcnt(10)
	v_mfma_f32_32x32x16_bf16 v[0:15], v[160:163], v[120:123], v[0:15]
	ds_read_b64_tr_b16 v[152:153], v177 offset:2048
	ds_read_b64_tr_b16 v[154:155], v177 offset:3072
	v_exp_f32_e32 v56, v56
	v_exp_f32_e32 v57, v57
	v_add_f32_e32 v130, v130, v56
	v_add_f32_e32 v131, v131, v57
	v_cvt_pk_bf16_f32 v108, v56, v57
	s_waitcnt lgkmcnt(10)
	v_mfma_f32_32x32x16_bf16 v[16:31], v[164:167], v[120:123], v[16:31]
	ds_read_b64_tr_b16 v[156:157], v177 offset:2560
	ds_read_b64_tr_b16 v[158:159], v177 offset:3584
	v_exp_f32_e32 v58, v58
	v_exp_f32_e32 v59, v59
	v_add_f32_e32 v130, v130, v58
	v_add_f32_e32 v131, v131, v59
	v_cvt_pk_bf16_f32 v109, v58, v59
	s_waitcnt lgkmcnt(10)
	v_mfma_f32_32x32x16_bf16 v[0:15], v[168:171], v[124:127], v[0:15]
	ds_read_b64_tr_b16 v[160:161], v177 offset:4096
	ds_read_b64_tr_b16 v[162:163], v177 offset:5120
	v_exp_f32_e32 v60, v60
	v_exp_f32_e32 v61, v61
	v_add_f32_e32 v130, v130, v60
	v_add_f32_e32 v131, v131, v61
	v_cvt_pk_bf16_f32 v110, v60, v61
	s_waitcnt lgkmcnt(10)
	v_mfma_f32_32x32x16_bf16 v[16:31], v[172:175], v[124:127], v[16:31]
	ds_read_b64_tr_b16 v[164:165], v177 offset:4608
	ds_read_b64_tr_b16 v[166:167], v177 offset:5632
	v_exp_f32_e32 v62, v62
	v_exp_f32_e32 v63, v63
	v_add_f32_e32 v130, v130, v62
	v_add_f32_e32 v131, v131, v63
	v_cvt_pk_bf16_f32 v111, v62, v63
	s_waitcnt lgkmcnt(10)
	v_mfma_f32_32x32x16_bf16 v[0:15], v[144:147], v[96:99], v[0:15]
	ds_read_b64_tr_b16 v[168:169], v177 offset:6144
	ds_read_b64_tr_b16 v[170:171], v177 offset:7168
	v_exp_f32_e32 v64, v64
	v_exp_f32_e32 v65, v65
	v_add_f32_e32 v130, v130, v64
	v_add_f32_e32 v131, v131, v65
	v_cvt_pk_bf16_f32 v112, v64, v65
	v_exp_f32_e32 v66, v66
	v_exp_f32_e32 v67, v67
	v_add_f32_e32 v130, v130, v66
	v_add_f32_e32 v131, v131, v67
	v_cvt_pk_bf16_f32 v113, v66, v67
	s_waitcnt lgkmcnt(10)
	v_mfma_f32_32x32x16_bf16 v[16:31], v[148:151], v[96:99], v[16:31]
	ds_read_b64_tr_b16 v[172:173], v177 offset:6656
	ds_read_b64_tr_b16 v[174:175], v177 offset:7680
	v_exp_f32_e32 v68, v68
	v_exp_f32_e32 v69, v69
	v_add_f32_e32 v130, v130, v68
	v_add_f32_e32 v131, v131, v69
	v_cvt_pk_bf16_f32 v114, v68, v69
	v_exp_f32_e32 v70, v70
	v_exp_f32_e32 v71, v71
	v_add_f32_e32 v130, v130, v70
	v_add_f32_e32 v131, v131, v71
	v_cvt_pk_bf16_f32 v115, v70, v71
	s_waitcnt lgkmcnt(10)
	v_mfma_f32_32x32x16_bf16 v[0:15], v[152:155], v[100:103], v[0:15]
	v_exp_f32_e32 v72, v72
	v_exp_f32_e32 v73, v73
	v_add_f32_e32 v130, v130, v72
	v_add_f32_e32 v131, v131, v73
	v_cvt_pk_bf16_f32 v116, v72, v73
	v_exp_f32_e32 v74, v74
	v_exp_f32_e32 v75, v75
	v_add_f32_e32 v130, v130, v74
	v_add_f32_e32 v131, v131, v75
	v_cvt_pk_bf16_f32 v117, v74, v75
	s_waitcnt lgkmcnt(8)
	v_mfma_f32_32x32x16_bf16 v[16:31], v[156:159], v[100:103], v[16:31]
	v_exp_f32_e32 v76, v76
	v_exp_f32_e32 v77, v77
	v_add_f32_e32 v130, v130, v76
	v_add_f32_e32 v131, v131, v77
	v_cvt_pk_bf16_f32 v118, v76, v77
	v_exp_f32_e32 v78, v78
	v_exp_f32_e32 v79, v79
	v_add_f32_e32 v130, v130, v78
	v_add_f32_e32 v131, v131, v79
	v_cvt_pk_bf16_f32 v119, v78, v79
	s_waitcnt lgkmcnt(6)
	v_mfma_f32_32x32x16_bf16 v[0:15], v[160:163], v[104:107], v[0:15]
	v_exp_f32_e32 v80, v80
	v_exp_f32_e32 v81, v81
	v_add_f32_e32 v130, v130, v80
	v_add_f32_e32 v131, v131, v81
	v_cvt_pk_bf16_f32 v120, v80, v81
	v_exp_f32_e32 v82, v82
	v_exp_f32_e32 v83, v83
	v_add_f32_e32 v130, v130, v82
	v_add_f32_e32 v131, v131, v83
	v_cvt_pk_bf16_f32 v121, v82, v83
	s_waitcnt lgkmcnt(4)
	v_mfma_f32_32x32x16_bf16 v[16:31], v[164:167], v[104:107], v[16:31]
	v_exp_f32_e32 v84, v84
	v_exp_f32_e32 v85, v85
	v_add_f32_e32 v130, v130, v84
	v_add_f32_e32 v131, v131, v85
	v_cvt_pk_bf16_f32 v122, v84, v85
	v_exp_f32_e32 v86, v86
	v_exp_f32_e32 v87, v87
	v_add_f32_e32 v130, v130, v86
	v_add_f32_e32 v131, v131, v87
	v_cvt_pk_bf16_f32 v123, v86, v87
	s_waitcnt lgkmcnt(2)
	v_mfma_f32_32x32x16_bf16 v[0:15], v[168:171], v[108:111], v[0:15]
	v_exp_f32_e32 v88, v88
	v_exp_f32_e32 v89, v89
	v_add_f32_e32 v130, v130, v88
	v_add_f32_e32 v131, v131, v89
	v_cvt_pk_bf16_f32 v124, v88, v89
	v_exp_f32_e32 v90, v90
	v_exp_f32_e32 v91, v91
	v_add_f32_e32 v130, v130, v90
	v_add_f32_e32 v131, v131, v91
	v_cvt_pk_bf16_f32 v125, v90, v91
	s_waitcnt lgkmcnt(0)
	v_mfma_f32_32x32x16_bf16 v[16:31], v[172:175], v[108:111], v[16:31]
	v_exp_f32_e32 v92, v92
	v_exp_f32_e32 v93, v93
	v_add_f32_e32 v130, v130, v92
	v_add_f32_e32 v131, v131, v93
	v_cvt_pk_bf16_f32 v126, v92, v93
	v_exp_f32_e32 v94, v94
	v_exp_f32_e32 v95, v95
	v_add_f32_e32 v130, v130, v94
	v_add_f32_e32 v131, v131, v95
	v_cvt_pk_bf16_f32 v127, v94, v95
	v_add_u32_e32 v176, s70, v238
	ds_read_b64_tr_b16 v[144:145], v176 offset:8192
	ds_read_b64_tr_b16 v[146:147], v176 offset:9216
	ds_read_b64_tr_b16 v[148:149], v176 offset:8704
	ds_read_b64_tr_b16 v[150:151], v176 offset:9728
	ds_read_b64_tr_b16 v[152:153], v176 offset:10240
	ds_read_b64_tr_b16 v[154:155], v176 offset:11264
	ds_read_b64_tr_b16 v[156:157], v176 offset:10752
	ds_read_b64_tr_b16 v[158:159], v176 offset:11776
	ds_read_b64_tr_b16 v[160:161], v176 offset:12288
	ds_read_b64_tr_b16 v[162:163], v176 offset:13312
	ds_read_b64_tr_b16 v[164:165], v176 offset:12800
	ds_read_b64_tr_b16 v[166:167], v176 offset:13824
	s_waitcnt lgkmcnt(10)
	v_mfma_f32_32x32x16_bf16 v[0:15], v[144:147], v[112:115], v[0:15]
	ds_read_b64_tr_b16 v[168:169], v176 offset:14336
	ds_read_b64_tr_b16 v[170:171], v176 offset:15360
	s_waitcnt lgkmcnt(10)
	v_mfma_f32_32x32x16_bf16 v[16:31], v[148:151], v[112:115], v[16:31]
	ds_read_b64_tr_b16 v[172:173], v176 offset:14848
	ds_read_b64_tr_b16 v[174:175], v176 offset:15872
	s_waitcnt lgkmcnt(10)
	v_mfma_f32_32x32x16_bf16 v[0:15], v[152:155], v[116:119], v[0:15]
	s_waitcnt lgkmcnt(8)
	v_mfma_f32_32x32x16_bf16 v[16:31], v[156:159], v[116:119], v[16:31]
	s_waitcnt lgkmcnt(6)
	v_mfma_f32_32x32x16_bf16 v[0:15], v[160:163], v[120:123], v[0:15]
	s_waitcnt lgkmcnt(4)
	v_mfma_f32_32x32x16_bf16 v[16:31], v[164:167], v[120:123], v[16:31]
	s_waitcnt lgkmcnt(2)
	v_mfma_f32_32x32x16_bf16 v[0:15], v[168:171], v[124:127], v[0:15]
	s_waitcnt lgkmcnt(0)
	v_mfma_f32_32x32x16_bf16 v[16:31], v[172:175], v[124:127], v[16:31]
	global_load_dwordx2 v[32:33], v133, s[12:13] offset:0
	global_load_dwordx2 v[34:35], v133, s[12:13] offset:64
	global_load_dwordx2 v[36:37], v133, s[12:13] offset:16
	global_load_dwordx2 v[38:39], v133, s[12:13] offset:80
	global_load_dwordx2 v[40:41], v133, s[12:13] offset:32
	global_load_dwordx2 v[42:43], v133, s[12:13] offset:96
	global_load_dwordx2 v[44:45], v133, s[12:13] offset:48
	global_load_dwordx2 v[46:47], v133, s[12:13] offset:112
	v_add_f32_e32 v135, v130, v131
	v_mov_b32_e32 v128, v135
	s_nop 1
	v_permlane32_swap_b32_e32 v135, v128
	s_nop 1
	v_add_f32_e32 v135, v135, v128
	s_mov_b32 s0, 0x7149f2ca
	v_cmp_lt_f32_e32 vcc, 0xda24260, v135
	v_cmp_gt_f32_e64 s[76:77], s0, v135
	s_nop 1
	s_and_b64 s[76:77], s[76:77], vcc
	s_andn2_b64 s[76:77], exec, s[76:77]
	s_cmp_lg_u64 s[76:77], 0
	s_cselect_b32 s0, 1, 0
	v_mov_b32_e32 v128, s0
	v_lshrrev_b32_e32 v132, 6, v143
	v_lshlrev_b32_e32 v132, 2, v132
	v_add_u32_e32 v132, 131072, v132
	ds_write_b32 v132, v128
	s_waitcnt lgkmcnt(0)
	s_barrier
	v_mov_b32_e32 v132, 131072
	ds_read_b128 v[48:51], v132
	ds_read_b128 v[52:55], v132 offset:16
	v_rcp_f32_e32 v136, v135
	s_nop 0
	v_fma_f32 v128, -v135, v136, 1.0
	v_fma_f32 v136, v136, v128, v136
	s_waitcnt lgkmcnt(0)
	v_or_b32_e32 v48, v48, v49
	v_or3_b32 v48, v48, v50, v51
	v_or3_b32 v48, v48, v52, v53
	v_or3_b32 v48, v48, v54, v55
	s_nop 0
	v_readfirstlane_b32 s0, v48
	s_and_b32 s1, s9, 31
	s_lshl_b32 s1, 1, s1
	s_cmp_lg_u32 s0, 0
	s_cselect_b32 s1, s1, 0
	s_or_b32 s26, s26, s1
	s_waitcnt vmcnt(0)
	s_mov_b32 s0, 0xbfb8aa3b
	v_lshlrev_b32_e32 v56, 16, v32
	v_and_b32_e32 v57, 0xffff0000, v32
	v_lshlrev_b32_e32 v58, 16, v33
	v_and_b32_e32 v59, 0xffff0000, v33
	v_mul_f32_e32 v62, s0, v56
	v_mul_f32_e32 v63, s0, v57
	v_mul_f32_e32 v48, s0, v58
	v_mul_f32_e32 v49, s0, v59
	v_exp_f32_e32 v62, v62
	v_exp_f32_e32 v63, v63
	v_exp_f32_e32 v48, v48
	v_exp_f32_e32 v49, v49
	s_nop 0
	v_add_f32_e32 v62, 1.0, v62
	v_add_f32_e32 v63, 1.0, v63
	v_add_f32_e32 v48, 1.0, v48
	v_add_f32_e32 v49, 1.0, v49
	v_rcp_f32_e32 v62, v62
	v_rcp_f32_e32 v63, v63
	v_rcp_f32_e32 v48, v48
	v_rcp_f32_e32 v49, v49
	s_nop 0
	v_mul_f32_e32 v56, v56, v62
	v_mul_f32_e32 v57, v57, v63
	v_mul_f32_e32 v58, v58, v48
	v_mul_f32_e32 v59, v59, v49
	v_mul_f32_e32 v62, v0, v136
	v_mul_f32_e32 v63, v1, v136
	v_mul_f32_e32 v48, v2, v136
	v_mul_f32_e32 v49, v3, v136
	v_mul_f32_e32 v62, v62, v56
	v_mul_f32_e32 v63, v63, v57
	v_mul_f32_e32 v48, v48, v58
	v_mul_f32_e32 v49, v49, v59
	v_cvt_pk_bf16_f32 v60, v62, v63
	v_cvt_pk_bf16_f32 v61, v48, v49
	global_store_dwordx2 v134, v[60:61], s[14:15] offset:0
	s_nop 0
	v_lshlrev_b32_e32 v56, 16, v34
	v_and_b32_e32 v57, 0xffff0000, v34
	v_lshlrev_b32_e32 v58, 16, v35
	v_and_b32_e32 v59, 0xffff0000, v35
	v_mul_f32_e32 v62, s0, v56
	v_mul_f32_e32 v63, s0, v57
	v_mul_f32_e32 v48, s0, v58
	v_mul_f32_e32 v49, s0, v59
	v_exp_f32_e32 v62, v62
	v_exp_f32_e32 v63, v63
	v_exp_f32_e32 v48, v48
	v_exp_f32_e32 v49, v49
	s_nop 0
	v_add_f32_e32 v62, 1.0, v62
	v_add_f32_e32 v63, 1.0, v63
	v_add_f32_e32 v48, 1.0, v48
	v_add_f32_e32 v49, 1.0, v49
	v_rcp_f32_e32 v62, v62
	v_rcp_f32_e32 v63, v63
	v_rcp_f32_e32 v48, v48
	v_rcp_f32_e32 v49, v49
	s_nop 0
	v_mul_f32_e32 v56, v56, v62
	v_mul_f32_e32 v57, v57, v63
	v_mul_f32_e32 v58, v58, v48
	v_mul_f32_e32 v59, v59, v49
	v_mul_f32_e32 v62, v16, v136
	v_mul_f32_e32 v63, v17, v136
	v_mul_f32_e32 v48, v18, v136
	v_mul_f32_e32 v49, v19, v136
	v_mul_f32_e32 v62, v62, v56
	v_mul_f32_e32 v63, v63, v57
	v_mul_f32_e32 v48, v48, v58
	v_mul_f32_e32 v49, v49, v59
	v_cvt_pk_bf16_f32 v60, v62, v63
	v_cvt_pk_bf16_f32 v61, v48, v49
	global_store_dwordx2 v134, v[60:61], s[14:15] offset:64
	s_nop 0
	v_lshlrev_b32_e32 v56, 16, v36
	v_and_b32_e32 v57, 0xffff0000, v36
	v_lshlrev_b32_e32 v58, 16, v37
	v_and_b32_e32 v59, 0xffff0000, v37
	v_mul_f32_e32 v62, s0, v56
	v_mul_f32_e32 v63, s0, v57
	v_mul_f32_e32 v48, s0, v58
	v_mul_f32_e32 v49, s0, v59
	v_exp_f32_e32 v62, v62
	v_exp_f32_e32 v63, v63
	v_exp_f32_e32 v48, v48
	v_exp_f32_e32 v49, v49
	s_nop 0
	v_add_f32_e32 v62, 1.0, v62
	v_add_f32_e32 v63, 1.0, v63
	v_add_f32_e32 v48, 1.0, v48
	v_add_f32_e32 v49, 1.0, v49
	v_rcp_f32_e32 v62, v62
	v_rcp_f32_e32 v63, v63
	v_rcp_f32_e32 v48, v48
	v_rcp_f32_e32 v49, v49
	s_nop 0
	v_mul_f32_e32 v56, v56, v62
	v_mul_f32_e32 v57, v57, v63
	v_mul_f32_e32 v58, v58, v48
	v_mul_f32_e32 v59, v59, v49
	v_mul_f32_e32 v62, v4, v136
	v_mul_f32_e32 v63, v5, v136
	v_mul_f32_e32 v48, v6, v136
	v_mul_f32_e32 v49, v7, v136
	v_mul_f32_e32 v62, v62, v56
	v_mul_f32_e32 v63, v63, v57
	v_mul_f32_e32 v48, v48, v58
	v_mul_f32_e32 v49, v49, v59
	v_cvt_pk_bf16_f32 v60, v62, v63
	v_cvt_pk_bf16_f32 v61, v48, v49
	global_store_dwordx2 v134, v[60:61], s[14:15] offset:16
	s_nop 0
	v_lshlrev_b32_e32 v56, 16, v38
	v_and_b32_e32 v57, 0xffff0000, v38
	v_lshlrev_b32_e32 v58, 16, v39
	v_and_b32_e32 v59, 0xffff0000, v39
	v_mul_f32_e32 v62, s0, v56
	v_mul_f32_e32 v63, s0, v57
	v_mul_f32_e32 v48, s0, v58
	v_mul_f32_e32 v49, s0, v59
	v_exp_f32_e32 v62, v62
	v_exp_f32_e32 v63, v63
	v_exp_f32_e32 v48, v48
	v_exp_f32_e32 v49, v49
	s_nop 0
	v_add_f32_e32 v62, 1.0, v62
	v_add_f32_e32 v63, 1.0, v63
	v_add_f32_e32 v48, 1.0, v48
	v_add_f32_e32 v49, 1.0, v49
	v_rcp_f32_e32 v62, v62
	v_rcp_f32_e32 v63, v63
	v_rcp_f32_e32 v48, v48
	v_rcp_f32_e32 v49, v49
	s_nop 0
	v_mul_f32_e32 v56, v56, v62
	v_mul_f32_e32 v57, v57, v63
	v_mul_f32_e32 v58, v58, v48
	v_mul_f32_e32 v59, v59, v49
	v_mul_f32_e32 v62, v20, v136
	v_mul_f32_e32 v63, v21, v136
	v_mul_f32_e32 v48, v22, v136
	v_mul_f32_e32 v49, v23, v136
	v_mul_f32_e32 v62, v62, v56
	v_mul_f32_e32 v63, v63, v57
	v_mul_f32_e32 v48, v48, v58
	v_mul_f32_e32 v49, v49, v59
	v_cvt_pk_bf16_f32 v60, v62, v63
	v_cvt_pk_bf16_f32 v61, v48, v49
	global_store_dwordx2 v134, v[60:61], s[14:15] offset:80
	s_nop 0
	v_lshlrev_b32_e32 v56, 16, v40
	v_and_b32_e32 v57, 0xffff0000, v40
	v_lshlrev_b32_e32 v58, 16, v41
	v_and_b32_e32 v59, 0xffff0000, v41
	v_mul_f32_e32 v62, s0, v56
	v_mul_f32_e32 v63, s0, v57
	v_mul_f32_e32 v48, s0, v58
	v_mul_f32_e32 v49, s0, v59
	v_exp_f32_e32 v62, v62
	v_exp_f32_e32 v63, v63
	v_exp_f32_e32 v48, v48
	v_exp_f32_e32 v49, v49
	s_nop 0
	v_add_f32_e32 v62, 1.0, v62
	v_add_f32_e32 v63, 1.0, v63
	v_add_f32_e32 v48, 1.0, v48
	v_add_f32_e32 v49, 1.0, v49
	v_rcp_f32_e32 v62, v62
	v_rcp_f32_e32 v63, v63
	v_rcp_f32_e32 v48, v48
	v_rcp_f32_e32 v49, v49
	s_nop 0
	v_mul_f32_e32 v56, v56, v62
	v_mul_f32_e32 v57, v57, v63
	v_mul_f32_e32 v58, v58, v48
	v_mul_f32_e32 v59, v59, v49
	v_mul_f32_e32 v62, v8, v136
	v_mul_f32_e32 v63, v9, v136
	v_mul_f32_e32 v48, v10, v136
	v_mul_f32_e32 v49, v11, v136
	v_mul_f32_e32 v62, v62, v56
	v_mul_f32_e32 v63, v63, v57
	v_mul_f32_e32 v48, v48, v58
	v_mul_f32_e32 v49, v49, v59
	v_cvt_pk_bf16_f32 v60, v62, v63
	v_cvt_pk_bf16_f32 v61, v48, v49
	global_store_dwordx2 v134, v[60:61], s[14:15] offset:32
	s_nop 0
	v_lshlrev_b32_e32 v56, 16, v42
	v_and_b32_e32 v57, 0xffff0000, v42
	v_lshlrev_b32_e32 v58, 16, v43
	v_and_b32_e32 v59, 0xffff0000, v43
	v_mul_f32_e32 v62, s0, v56
	v_mul_f32_e32 v63, s0, v57
	v_mul_f32_e32 v48, s0, v58
	v_mul_f32_e32 v49, s0, v59
	v_exp_f32_e32 v62, v62
	v_exp_f32_e32 v63, v63
	v_exp_f32_e32 v48, v48
	v_exp_f32_e32 v49, v49
	s_nop 0
	v_add_f32_e32 v62, 1.0, v62
	v_add_f32_e32 v63, 1.0, v63
	v_add_f32_e32 v48, 1.0, v48
	v_add_f32_e32 v49, 1.0, v49
	v_rcp_f32_e32 v62, v62
	v_rcp_f32_e32 v63, v63
	v_rcp_f32_e32 v48, v48
	v_rcp_f32_e32 v49, v49
	s_nop 0
	v_mul_f32_e32 v56, v56, v62
	v_mul_f32_e32 v57, v57, v63
	v_mul_f32_e32 v58, v58, v48
	v_mul_f32_e32 v59, v59, v49
	v_mul_f32_e32 v62, v24, v136
	v_mul_f32_e32 v63, v25, v136
	v_mul_f32_e32 v48, v26, v136
	v_mul_f32_e32 v49, v27, v136
	v_mul_f32_e32 v62, v62, v56
	v_mul_f32_e32 v63, v63, v57
	v_mul_f32_e32 v48, v48, v58
	v_mul_f32_e32 v49, v49, v59
	v_cvt_pk_bf16_f32 v60, v62, v63
	v_cvt_pk_bf16_f32 v61, v48, v49
	global_store_dwordx2 v134, v[60:61], s[14:15] offset:96
	s_nop 0
	v_lshlrev_b32_e32 v56, 16, v44
	v_and_b32_e32 v57, 0xffff0000, v44
	v_lshlrev_b32_e32 v58, 16, v45
	v_and_b32_e32 v59, 0xffff0000, v45
	v_mul_f32_e32 v62, s0, v56
	v_mul_f32_e32 v63, s0, v57
	v_mul_f32_e32 v48, s0, v58
	v_mul_f32_e32 v49, s0, v59
	v_exp_f32_e32 v62, v62
	v_exp_f32_e32 v63, v63
	v_exp_f32_e32 v48, v48
	v_exp_f32_e32 v49, v49
	s_nop 0
	v_add_f32_e32 v62, 1.0, v62
	v_add_f32_e32 v63, 1.0, v63
	v_add_f32_e32 v48, 1.0, v48
	v_add_f32_e32 v49, 1.0, v49
	v_rcp_f32_e32 v62, v62
	v_rcp_f32_e32 v63, v63
	v_rcp_f32_e32 v48, v48
	v_rcp_f32_e32 v49, v49
	s_nop 0
	v_mul_f32_e32 v56, v56, v62
	v_mul_f32_e32 v57, v57, v63
	v_mul_f32_e32 v58, v58, v48
	v_mul_f32_e32 v59, v59, v49
	v_mul_f32_e32 v62, v12, v136
	v_mul_f32_e32 v63, v13, v136
	v_mul_f32_e32 v48, v14, v136
	v_mul_f32_e32 v49, v15, v136
	v_mul_f32_e32 v62, v62, v56
	v_mul_f32_e32 v63, v63, v57
	v_mul_f32_e32 v48, v48, v58
	v_mul_f32_e32 v49, v49, v59
	v_cvt_pk_bf16_f32 v60, v62, v63
	v_cvt_pk_bf16_f32 v61, v48, v49
	global_store_dwordx2 v134, v[60:61], s[14:15] offset:48
	s_nop 0
	v_lshlrev_b32_e32 v56, 16, v46
	v_and_b32_e32 v57, 0xffff0000, v46
	v_lshlrev_b32_e32 v58, 16, v47
	v_and_b32_e32 v59, 0xffff0000, v47
	v_mul_f32_e32 v62, s0, v56
	v_mul_f32_e32 v63, s0, v57
	v_mul_f32_e32 v48, s0, v58
	v_mul_f32_e32 v49, s0, v59
	v_exp_f32_e32 v62, v62
	v_exp_f32_e32 v63, v63
	v_exp_f32_e32 v48, v48
	v_exp_f32_e32 v49, v49
	s_nop 0
	v_add_f32_e32 v62, 1.0, v62
	v_add_f32_e32 v63, 1.0, v63
	v_add_f32_e32 v48, 1.0, v48
	v_add_f32_e32 v49, 1.0, v49
	v_rcp_f32_e32 v62, v62
	v_rcp_f32_e32 v63, v63
	v_rcp_f32_e32 v48, v48
	v_rcp_f32_e32 v49, v49
	s_nop 0
	v_mul_f32_e32 v56, v56, v62
	v_mul_f32_e32 v57, v57, v63
	v_mul_f32_e32 v58, v58, v48
	v_mul_f32_e32 v59, v59, v49
	v_mul_f32_e32 v62, v28, v136
	v_mul_f32_e32 v63, v29, v136
	v_mul_f32_e32 v48, v30, v136
	v_mul_f32_e32 v49, v31, v136
	v_mul_f32_e32 v62, v62, v56
	v_mul_f32_e32 v63, v63, v57
	v_mul_f32_e32 v48, v48, v58
	v_mul_f32_e32 v49, v49, v59
	v_cvt_pk_bf16_f32 v60, v62, v63
	v_cvt_pk_bf16_f32 v61, v48, v49
	global_store_dwordx2 v134, v[60:61], s[14:15] offset:112
	s_nop 0
	s_branch .Lat_next
.Lat_done:
	s_mov_b64 exec, -1

	.amdhsa_kernel _Z14fwd_megakernel6Params
		.amdhsa_group_segment_fixed_size 0
		.amdhsa_private_segment_fixed_size 0
		.amdhsa_kernarg_size 448
		.amdhsa_user_sgpr_count 2
		.amdhsa_user_sgpr_dispatch_ptr 0
		.amdhsa_user_sgpr_queue_ptr 0
		.amdhsa_user_sgpr_kernarg_segment_ptr 1
		.amdhsa_user_sgpr_dispatch_id 0
		.amdhsa_user_sgpr_kernarg_preload_length 0
		.amdhsa_user_sgpr_kernarg_preload_offset 0
		.amdhsa_user_sgpr_private_segment_size 0
		.amdhsa_uses_dynamic_stack 0
		.amdhsa_enable_private_segment 0
		.amdhsa_system_sgpr_workgroup_id_x 1
		.amdhsa_system_sgpr_workgroup_id_y 0
		.amdhsa_system_sgpr_workgroup_id_z 0
		.amdhsa_system_sgpr_workgroup_info 0
		.amdhsa_system_vgpr_workitem_id 2
		.amdhsa_next_free_vgpr 256
		.amdhsa_next_free_sgpr 102
		.amdhsa_accum_offset 256
		.amdhsa_reserve_vcc 1
		.amdhsa_float_round_mode_32 0
		.amdhsa_float_round_mode_16_64 0
		.amdhsa_float_denorm_mode_32 3
		.amdhsa_float_denorm_mode_16_64 3
		.amdhsa_dx10_clamp 1
		.amdhsa_ieee_mode 1
		.amdhsa_fp16_overflow 0
		.amdhsa_tg_split 0
		.amdhsa_exception_fp_ieee_invalid_op 0
		.amdhsa_exception_fp_denorm_src 0
		.amdhsa_exception_fp_ieee_div_zero 0
		.amdhsa_exception_fp_ieee_overflow 0
		.amdhsa_exception_fp_ieee_underflow 0
		.amdhsa_exception_fp_ieee_inexact 0
		.amdhsa_exception_int_div_zero 0
	.end_amdhsa_kernel

amdhsa.kernels:
  - .agpr_count:     0
    .args:
      - .offset:         0
        .size:           192
        .value_kind:     by_value
      - .offset:         192
        .size:           4
        .value_kind:     hidden_block_count_x
      - .offset:         196
        .size:           4
        .value_kind:     hidden_block_count_y
      - .offset:         200
        .size:           4
        .value_kind:     hidden_block_count_z
      - .offset:         204
        .size:           2
        .value_kind:     hidden_group_size_x
      - .offset:         206
        .size:           2
        .value_kind:     hidden_group_size_y
      - .offset:         208
        .size:           2
        .value_kind:     hidden_group_size_z
      - .offset:         210
        .size:           2
        .value_kind:     hidden_remainder_x
      - .offset:         212
        .size:           2
        .value_kind:     hidden_remainder_y
      - .offset:         214
        .size:           2
        .value_kind:     hidden_remainder_z
      - .offset:         232
        .size:           8
        .value_kind:     hidden_global_offset_x
      - .offset:         240
        .size:           8
        .value_kind:     hidden_global_offset_y
      - .offset:         248
        .size:           8
        .value_kind:     hidden_global_offset_z
      - .offset:         256
        .size:           2
        .value_kind:     hidden_grid_dims
      - .offset:         280
        .size:           8
        .value_kind:     hidden_multigrid_sync_arg
      - .offset:         312
        .size:           4
        .value_kind:     hidden_dynamic_lds_size
    .group_segment_fixed_size: 0
    .kernarg_segment_align: 8
    .kernarg_segment_size: 448
    .language:       OpenCL C
    .language_version:
      - 2
      - 0
    .max_flat_workgroup_size: 512
    .name:           _Z14fwd_megakernel6Params
    .private_segment_fixed_size: 0
    .sgpr_count:     108
    .sgpr_spill_count: 157
    .symbol:         _Z14fwd_megakernel6Params.kd
    .uniform_work_group_size: 1
    .uses_dynamic_stack: false
    .vgpr_count:     256
    .vgpr_spill_count: 0
    .wavefront_size: 64
